# speedup vs baseline: 1.0537x; 1.0104x over previous
; #define WAIT_V(n) asm volatile("s_waitcnt vmcnt(" #n ")" ::: "memory")
; #define WAIT_L(n) asm volatile("s_waitcnt lgkmcnt(" #n ")" ::: "memory")
; #define BAR __builtin_amdgcn_s_barrier()
; #define SCHED __builtin_amdgcn_sched_barrier(0)
;     ...
;     LDB(B0, 0, 0); SCHED; LDA(At, 0, 0); STAGE(SA(1, 1), A, brow + HALF, t + 1);
;     WAIT_L(8); BAR; WAIT_L(0); MMA(0, 0, At, B0); BAR; SCHED;
;     LDB(B1, 0, 1); STAGE(SB(0, 0), Bt, bcol, t + 2);
;     BAR; WAIT_L(0); MMA(0, 1, At, B1); BAR;
;     LDA(At, 0, 1); STAGE(SA(0, 0), A, brow, t + 2);
;     BAR; WAIT_L(0); MMA(1, 0, At, B0); BAR; SCHED;
;     STAGE(SB(0, 1), Bt, bcol1, t + 2);
;     WAIT_V(6); BAR; MMA(1, 1, At, B1); BAR;
.LBB0_69:
	ds_read_b128 v[166:169], v162
	ds_read_b128 v[170:173], v162 offset:1024
	ds_read_b128 v[174:177], v162 offset:2048
	ds_read_b128 v[178:181], v162 offset:3072
	v_add_u32_e32 v163, 0xc000, v147
	s_add_u32 m0, s11, 0xc000
	ds_read_b128 v[186:189], v144
	ds_read_b128 v[190:193], v144 offset:1024
	ds_read_b128 v[194:197], v141
	ds_read_b128 v[198:201], v141 offset:1024
	ds_read_b128 v[202:205], v140
	ds_read_b128 v[206:209], v140 offset:1024
	ds_read_b128 v[210:213], v139
	ds_read_b128 v[214:217], v139 offset:1024
	global_load_lds_dwordx4 v151, s[64:65]
	s_add_u32 s64, s64, 0x100
	s_addc_u32 s65, s65, 0
	v_add_u32_e32 v164, 0xe000, v147
	s_add_u32 m0, s11, 0xe000
	s_nop 0
	global_load_lds_dwordx4 v153, s[66:67]
	s_add_u32 s66, s66, 0x100
	s_addc_u32 s67, s67, 0
	s_waitcnt lgkmcnt(8)
	s_barrier
	s_waitcnt lgkmcnt(0)
	v_mfma_f32_16x16x32_bf16 v[124:127], v[166:169], v[186:189], v[124:127]
	v_mfma_f32_16x16x32_bf16 v[120:123], v[174:177], v[186:189], v[120:123]
	v_mfma_f32_16x16x32_bf16 v[116:119], v[166:169], v[194:197], v[116:119]
	v_mfma_f32_16x16x32_bf16 v[112:115], v[174:177], v[194:197], v[112:115]
	v_mfma_f32_16x16x32_bf16 v[108:111], v[166:169], v[202:205], v[108:111]
	v_mfma_f32_16x16x32_bf16 v[104:107], v[174:177], v[202:205], v[104:107]
	v_mfma_f32_16x16x32_bf16 v[100:103], v[166:169], v[210:213], v[100:103]
	v_mfma_f32_16x16x32_bf16 v[96:99], v[174:177], v[210:213], v[96:99]
	v_mfma_f32_16x16x32_bf16 v[124:127], v[170:173], v[190:193], v[124:127]
	v_mfma_f32_16x16x32_bf16 v[120:123], v[178:181], v[190:193], v[120:123]
	v_mfma_f32_16x16x32_bf16 v[116:119], v[170:173], v[198:201], v[116:119]
	v_mfma_f32_16x16x32_bf16 v[112:115], v[178:181], v[198:201], v[112:115]
	v_mfma_f32_16x16x32_bf16 v[108:111], v[170:173], v[206:209], v[108:111]
	v_mfma_f32_16x16x32_bf16 v[104:107], v[178:181], v[206:209], v[104:107]
	v_mfma_f32_16x16x32_bf16 v[100:103], v[170:173], v[214:217], v[100:103]
	v_mfma_f32_16x16x32_bf16 v[96:99], v[178:181], v[214:217], v[96:99]
	s_barrier
	s_add_u32 m0, s11, s33
	ds_read_b128 v[218:221], v161
	ds_read_b128 v[222:225], v161 offset:1024
	ds_read_b128 v[226:229], v161 offset:2048
	ds_read_b128 v[240:243], v161 offset:3072
	global_load_lds_dwordx4 v149, s[68:69]
	s_add_u32 s68, s68, 0x100
	s_addc_u32 s69, s69, 0
	s_add_u32 m0, s11, 0x2000
	s_add_u32 m0, m0, s33
	s_nop 0
	global_load_lds_dwordx4 v150, s[70:71]
	s_add_u32 s70, s70, 0x100
	s_addc_u32 s71, s71, 0
	s_barrier
	s_waitcnt lgkmcnt(0)
	v_mfma_f32_16x16x32_bf16 v[92:95], v[218:221], v[186:189], v[92:95]
	v_mfma_f32_16x16x32_bf16 v[88:91], v[226:229], v[186:189], v[88:91]
	v_mfma_f32_16x16x32_bf16 v[84:87], v[218:221], v[194:197], v[84:87]
	v_mfma_f32_16x16x32_bf16 v[80:83], v[226:229], v[194:197], v[80:83]
	v_mfma_f32_16x16x32_bf16 v[76:79], v[218:221], v[202:205], v[76:79]
	v_mfma_f32_16x16x32_bf16 v[72:75], v[226:229], v[202:205], v[72:75]
	v_mfma_f32_16x16x32_bf16 v[68:71], v[218:221], v[210:213], v[68:71]
	v_mfma_f32_16x16x32_bf16 v[64:67], v[226:229], v[210:213], v[64:67]
	v_mfma_f32_16x16x32_bf16 v[92:95], v[222:225], v[190:193], v[92:95]
	v_mfma_f32_16x16x32_bf16 v[88:91], v[240:243], v[190:193], v[88:91]
	v_mfma_f32_16x16x32_bf16 v[84:87], v[222:225], v[198:201], v[84:87]
	v_mfma_f32_16x16x32_bf16 v[80:83], v[240:243], v[198:201], v[80:83]
	v_mfma_f32_16x16x32_bf16 v[76:79], v[222:225], v[206:209], v[76:79]
	v_mfma_f32_16x16x32_bf16 v[72:75], v[240:243], v[206:209], v[72:75]
	v_mfma_f32_16x16x32_bf16 v[68:71], v[222:225], v[214:217], v[68:71]
	v_mfma_f32_16x16x32_bf16 v[64:67], v[240:243], v[214:217], v[64:67]
	s_mov_b32 m0, s11
	s_barrier
	ds_read_b128 v[186:189], v144 offset:16384
	ds_read_b128 v[190:193], v144 offset:17408
	ds_read_b128 v[194:197], v141 offset:16384
	ds_read_b128 v[198:201], v141 offset:17408
	ds_read_b128 v[202:205], v140 offset:16384
	ds_read_b128 v[206:209], v140 offset:17408
	ds_read_b128 v[210:213], v139 offset:16384
	ds_read_b128 v[214:217], v139 offset:17408
	global_load_lds_dwordx4 v151, s[72:73]
	s_add_u32 s72, s72, 0x100
	s_addc_u32 s73, s73, 0
	s_add_u32 m0, s11, 0x2000
	s_nop 0
	global_load_lds_dwordx4 v153, s[74:75]
	s_add_u32 s74, s74, 0x100
	s_addc_u32 s75, s75, 0
	s_barrier
	s_waitcnt lgkmcnt(0)
	v_mfma_f32_16x16x32_bf16 v[60:63], v[166:169], v[186:189], v[60:63]
	v_mfma_f32_16x16x32_bf16 v[56:59], v[174:177], v[186:189], v[56:59]
	v_mfma_f32_16x16x32_bf16 v[52:55], v[166:169], v[194:197], v[52:55]
	v_mfma_f32_16x16x32_bf16 v[48:51], v[174:177], v[194:197], v[48:51]
	v_mfma_f32_16x16x32_bf16 v[44:47], v[166:169], v[202:205], v[44:47]
	v_mfma_f32_16x16x32_bf16 v[40:43], v[174:177], v[202:205], v[40:43]
	v_mfma_f32_16x16x32_bf16 v[36:39], v[166:169], v[210:213], v[36:39]
	v_mfma_f32_16x16x32_bf16 v[32:35], v[174:177], v[210:213], v[32:35]
	v_mfma_f32_16x16x32_bf16 v[60:63], v[170:173], v[190:193], v[60:63]
	v_mfma_f32_16x16x32_bf16 v[56:59], v[178:181], v[190:193], v[56:59]
	v_mfma_f32_16x16x32_bf16 v[52:55], v[170:173], v[198:201], v[52:55]
	v_mfma_f32_16x16x32_bf16 v[48:51], v[178:181], v[198:201], v[48:51]
	v_mfma_f32_16x16x32_bf16 v[44:47], v[170:173], v[206:209], v[44:47]
	v_mfma_f32_16x16x32_bf16 v[40:43], v[178:181], v[206:209], v[40:43]
	v_mfma_f32_16x16x32_bf16 v[36:39], v[170:173], v[214:217], v[36:39]
	v_mfma_f32_16x16x32_bf16 v[32:35], v[178:181], v[214:217], v[32:35]
	s_barrier
	s_add_u32 m0, s11, s53
	s_nop 0
	global_load_lds_dwordx4 v149, s[76:77]
	s_add_u32 s76, s76, 0x100
	s_addc_u32 s77, s77, 0
	s_add_u32 m0, s11, 0x2000
	s_add_u32 m0, m0, s53
	s_nop 0
	global_load_lds_dwordx4 v150, s[78:79]
	s_add_u32 s78, s78, 0x100
	s_addc_u32 s79, s79, 0
	s_waitcnt vmcnt(6)
	s_barrier
; #define WAIT_V(n) asm volatile("s_waitcnt vmcnt(" #n ")" ::: "memory")
; #define WAIT_L(n) asm volatile("s_waitcnt lgkmcnt(" #n ")" ::: "memory")
; #define BAR __builtin_amdgcn_s_barrier()
; #define SCHED __builtin_amdgcn_sched_barrier(0)
;     ...
;     WAIT_V(6); BAR; MMA(1, 1, At, B1); BAR;
;     LDB(B0, 1, 0); SCHED; LDA(At, 1, 0); STAGE(SA(0, 1), A, brow + HALF, t + 2);
;     WAIT_L(8); BAR; WAIT_L(0); MMA(0, 0, At, B0); BAR; SCHED;
;     LDB(B1, 1, 1); STAGE(SB(1, 0), Bt, bcol, t + 3);
;     BAR; WAIT_L(0); MMA(0, 1, At, B1); BAR;
;     LDA(At, 1, 1); STAGE(SA(1, 0), A, brow, t + 3);
	v_mfma_f32_16x16x32_bf16 v[28:31], v[218:221], v[186:189], v[28:31]
	v_mfma_f32_16x16x32_bf16 v[24:27], v[226:229], v[186:189], v[24:27]
	v_mfma_f32_16x16x32_bf16 v[20:23], v[218:221], v[194:197], v[20:23]
	v_mfma_f32_16x16x32_bf16 v[16:19], v[226:229], v[194:197], v[16:19]
	v_mfma_f32_16x16x32_bf16 v[12:15], v[218:221], v[202:205], v[12:15]
	v_mfma_f32_16x16x32_bf16 v[8:11], v[226:229], v[202:205], v[8:11]
	v_mfma_f32_16x16x32_bf16 v[4:7], v[218:221], v[210:213], v[4:7]
	v_mfma_f32_16x16x32_bf16 v[0:3], v[226:229], v[210:213], v[0:3]
	v_mfma_f32_16x16x32_bf16 v[28:31], v[222:225], v[190:193], v[28:31]
	v_mfma_f32_16x16x32_bf16 v[24:27], v[240:243], v[190:193], v[24:27]
	v_mfma_f32_16x16x32_bf16 v[20:23], v[222:225], v[198:201], v[20:23]
	v_mfma_f32_16x16x32_bf16 v[16:19], v[240:243], v[198:201], v[16:19]
	v_mfma_f32_16x16x32_bf16 v[12:15], v[222:225], v[206:209], v[12:15]
	v_mfma_f32_16x16x32_bf16 v[8:11], v[240:243], v[206:209], v[8:11]
	v_mfma_f32_16x16x32_bf16 v[4:7], v[222:225], v[214:217], v[4:7]
	v_mfma_f32_16x16x32_bf16 v[0:3], v[240:243], v[214:217], v[0:3]
	s_barrier
	ds_read_b128 v[166:169], v152
	ds_read_b128 v[170:173], v152 offset:1024
	ds_read_b128 v[174:177], v152 offset:2048
	ds_read_b128 v[178:181], v152 offset:3072
	s_add_u32 m0, s11, 0x4000
	ds_read_b128 v[186:189], v144 offset:32768
	ds_read_b128 v[190:193], v144 offset:33792
	ds_read_b128 v[194:197], v141 offset:32768
	ds_read_b128 v[198:201], v141 offset:33792
	ds_read_b128 v[202:205], v140 offset:32768
	ds_read_b128 v[206:209], v140 offset:33792
	ds_read_b128 v[210:213], v139 offset:32768
	ds_read_b128 v[214:217], v139 offset:33792
	global_load_lds_dwordx4 v151, s[80:81]
	s_add_u32 s80, s80, 0x100
	s_addc_u32 s81, s81, 0
	s_add_u32 m0, s11, 0x6000
	s_nop 0
	global_load_lds_dwordx4 v153, s[82:83]
	s_add_u32 s82, s82, 0x100
	s_addc_u32 s83, s83, 0
	s_waitcnt lgkmcnt(8)
	s_barrier
	s_waitcnt lgkmcnt(0)
	v_mfma_f32_16x16x32_bf16 v[124:127], v[166:169], v[186:189], v[124:127]
	v_mfma_f32_16x16x32_bf16 v[120:123], v[174:177], v[186:189], v[120:123]
	v_mfma_f32_16x16x32_bf16 v[116:119], v[166:169], v[194:197], v[116:119]
	v_mfma_f32_16x16x32_bf16 v[112:115], v[174:177], v[194:197], v[112:115]
	v_mfma_f32_16x16x32_bf16 v[108:111], v[166:169], v[202:205], v[108:111]
	v_mfma_f32_16x16x32_bf16 v[104:107], v[174:177], v[202:205], v[104:107]
	v_mfma_f32_16x16x32_bf16 v[100:103], v[166:169], v[210:213], v[100:103]
	v_mfma_f32_16x16x32_bf16 v[96:99], v[174:177], v[210:213], v[96:99]
	v_mfma_f32_16x16x32_bf16 v[124:127], v[170:173], v[190:193], v[124:127]
	v_mfma_f32_16x16x32_bf16 v[120:123], v[178:181], v[190:193], v[120:123]
	v_mfma_f32_16x16x32_bf16 v[116:119], v[170:173], v[198:201], v[116:119]
	v_mfma_f32_16x16x32_bf16 v[112:115], v[178:181], v[198:201], v[112:115]
	v_mfma_f32_16x16x32_bf16 v[108:111], v[170:173], v[206:209], v[108:111]
	v_mfma_f32_16x16x32_bf16 v[104:107], v[178:181], v[206:209], v[104:107]
	v_mfma_f32_16x16x32_bf16 v[100:103], v[170:173], v[214:217], v[100:103]
	v_mfma_f32_16x16x32_bf16 v[96:99], v[178:181], v[214:217], v[96:99]
	s_barrier
	s_add_u32 m0, s11, s54
	ds_read_b128 v[218:221], v148
	ds_read_b128 v[222:225], v148 offset:1024
	ds_read_b128 v[226:229], v148 offset:2048
	ds_read_b128 v[240:243], v148 offset:3072
	global_load_lds_dwordx4 v149, s[84:85]
	s_add_u32 s84, s84, 0x100
	s_addc_u32 s85, s85, 0
	s_add_u32 m0, s11, 0x2000
	s_add_u32 m0, m0, s54
	s_nop 0
	global_load_lds_dwordx4 v150, s[86:87]
	s_add_u32 s86, s86, 0x100
	s_addc_u32 s87, s87, 0
	s_barrier
	s_waitcnt lgkmcnt(0)
	v_mfma_f32_16x16x32_bf16 v[92:95], v[218:221], v[186:189], v[92:95]
	v_mfma_f32_16x16x32_bf16 v[88:91], v[226:229], v[186:189], v[88:91]
	v_mfma_f32_16x16x32_bf16 v[84:87], v[218:221], v[194:197], v[84:87]
	v_mfma_f32_16x16x32_bf16 v[80:83], v[226:229], v[194:197], v[80:83]
	v_mfma_f32_16x16x32_bf16 v[76:79], v[218:221], v[202:205], v[76:79]
	v_mfma_f32_16x16x32_bf16 v[72:75], v[226:229], v[202:205], v[72:75]
	v_mfma_f32_16x16x32_bf16 v[68:71], v[218:221], v[210:213], v[68:71]
	v_mfma_f32_16x16x32_bf16 v[64:67], v[226:229], v[210:213], v[64:67]
	v_mfma_f32_16x16x32_bf16 v[92:95], v[222:225], v[190:193], v[92:95]
	v_mfma_f32_16x16x32_bf16 v[88:91], v[240:243], v[190:193], v[88:91]
	v_mfma_f32_16x16x32_bf16 v[84:87], v[222:225], v[198:201], v[84:87]
	v_mfma_f32_16x16x32_bf16 v[80:83], v[240:243], v[198:201], v[80:83]
	v_mfma_f32_16x16x32_bf16 v[76:79], v[222:225], v[206:209], v[76:79]
	v_mfma_f32_16x16x32_bf16 v[72:75], v[240:243], v[206:209], v[72:75]
	v_mfma_f32_16x16x32_bf16 v[68:71], v[222:225], v[214:217], v[68:71]
	v_mfma_f32_16x16x32_bf16 v[64:67], v[240:243], v[214:217], v[64:67]
	s_add_u32 m0, s11, 0x8000
	s_barrier
	ds_read_b128 v[186:189], v144 offset:49152
	ds_read_b128 v[190:193], v144 offset:50176
	ds_read_b128 v[194:197], v141 offset:49152
	ds_read_b128 v[198:201], v141 offset:50176
	ds_read_b128 v[202:205], v140 offset:49152
	ds_read_b128 v[206:209], v140 offset:50176
	ds_read_b128 v[210:213], v139 offset:49152
	ds_read_b128 v[214:217], v139 offset:50176
	global_load_lds_dwordx4 v151, s[88:89]
	s_add_u32 s88, s88, 0x100
	s_addc_u32 s89, s89, 0
	s_add_u32 m0, s11, 0xa000
	s_nop 0
	global_load_lds_dwordx4 v153, s[90:91]
	s_add_u32 s90, s90, 0x100
	s_addc_u32 s91, s91, 0
	s_barrier
; #define WAIT_V(n) asm volatile("s_waitcnt vmcnt(" #n ")" ::: "memory")
; #define WAIT_L(n) asm volatile("s_waitcnt lgkmcnt(" #n ")" ::: "memory")
; #define BAR __builtin_amdgcn_s_barrier()
; #define SCHED __builtin_amdgcn_sched_barrier(0)
;     ...
;     BAR; WAIT_L(0); MMA(1, 0, At, B0); BAR; SCHED;
;     STAGE(SB(1, 1), Bt, bcol1, t + 3);
;     WAIT_V(6); BAR; MMA(1, 1, At, B1); BAR;
;   }
;   { LDB(B0, 0, 0); LDA(At, 0, 0); STAGE(SA(1, 1), A, brow + HALF, nt - 1);
;     BAR; WAIT_L(0); MMA(0, 0, At, B0); BAR;
	s_waitcnt lgkmcnt(0)
	v_mfma_f32_16x16x32_bf16 v[60:63], v[166:169], v[186:189], v[60:63]
	v_mfma_f32_16x16x32_bf16 v[56:59], v[174:177], v[186:189], v[56:59]
	v_mfma_f32_16x16x32_bf16 v[52:55], v[166:169], v[194:197], v[52:55]
	v_mfma_f32_16x16x32_bf16 v[48:51], v[174:177], v[194:197], v[48:51]
	v_mfma_f32_16x16x32_bf16 v[44:47], v[166:169], v[202:205], v[44:47]
	v_mfma_f32_16x16x32_bf16 v[40:43], v[174:177], v[202:205], v[40:43]
	v_mfma_f32_16x16x32_bf16 v[36:39], v[166:169], v[210:213], v[36:39]
	v_mfma_f32_16x16x32_bf16 v[32:35], v[174:177], v[210:213], v[32:35]
	v_mfma_f32_16x16x32_bf16 v[60:63], v[170:173], v[190:193], v[60:63]
	v_mfma_f32_16x16x32_bf16 v[56:59], v[178:181], v[190:193], v[56:59]
	v_mfma_f32_16x16x32_bf16 v[52:55], v[170:173], v[198:201], v[52:55]
	v_mfma_f32_16x16x32_bf16 v[48:51], v[178:181], v[198:201], v[48:51]
	v_mfma_f32_16x16x32_bf16 v[44:47], v[170:173], v[206:209], v[44:47]
	v_mfma_f32_16x16x32_bf16 v[40:43], v[178:181], v[206:209], v[40:43]
	v_mfma_f32_16x16x32_bf16 v[36:39], v[170:173], v[214:217], v[36:39]
	v_mfma_f32_16x16x32_bf16 v[32:35], v[178:181], v[214:217], v[32:35]
	s_barrier
	s_add_u32 m0, s11, s55
	s_nop 0
	global_load_lds_dwordx4 v149, s[92:93]
	s_add_u32 s92, s92, 0x100
	s_addc_u32 s93, s93, 0
	s_add_u32 m0, s11, 0x2000
	s_add_u32 m0, m0, s55
	s_nop 0
	global_load_lds_dwordx4 v150, s[94:95]
	s_add_u32 s94, s94, 0x100
	s_addc_u32 s95, s95, 0
	s_waitcnt vmcnt(6)
	s_barrier
	v_mfma_f32_16x16x32_bf16 v[28:31], v[218:221], v[186:189], v[28:31]
	v_mfma_f32_16x16x32_bf16 v[24:27], v[226:229], v[186:189], v[24:27]
	v_mfma_f32_16x16x32_bf16 v[20:23], v[218:221], v[194:197], v[20:23]
	v_mfma_f32_16x16x32_bf16 v[16:19], v[226:229], v[194:197], v[16:19]
	v_mfma_f32_16x16x32_bf16 v[12:15], v[218:221], v[202:205], v[12:15]
	v_mfma_f32_16x16x32_bf16 v[8:11], v[226:229], v[202:205], v[8:11]
	v_mfma_f32_16x16x32_bf16 v[4:7], v[218:221], v[210:213], v[4:7]
	v_mfma_f32_16x16x32_bf16 v[0:3], v[226:229], v[210:213], v[0:3]
	v_mfma_f32_16x16x32_bf16 v[28:31], v[222:225], v[190:193], v[28:31]
	v_mfma_f32_16x16x32_bf16 v[24:27], v[240:243], v[190:193], v[24:27]
	v_mfma_f32_16x16x32_bf16 v[20:23], v[222:225], v[198:201], v[20:23]
	v_mfma_f32_16x16x32_bf16 v[16:19], v[240:243], v[198:201], v[16:19]
	v_mfma_f32_16x16x32_bf16 v[12:15], v[222:225], v[206:209], v[12:15]
	v_mfma_f32_16x16x32_bf16 v[8:11], v[240:243], v[206:209], v[8:11]
	v_mfma_f32_16x16x32_bf16 v[4:7], v[222:225], v[214:217], v[4:7]
	v_mfma_f32_16x16x32_bf16 v[0:3], v[240:243], v[214:217], v[0:3]
	s_add_i32 s10, s10, 2
	s_add_u32 s8, s8, 0x100
	s_addc_u32 s9, s9, 0
	s_cmp_lt_u32 s10, 60
	s_barrier
	s_cbranch_scc1 .LBB0_69
	v_readlane_b32 s64, v254, 0
	v_readlane_b32 s65, v254, 1
	v_readlane_b32 s66, v254, 2
	v_readlane_b32 s67, v254, 3
	v_readlane_b32 s68, v254, 4
	v_readlane_b32 s69, v254, 5
	v_readlane_b32 s70, v254, 6
	v_readlane_b32 s71, v254, 7
	v_readlane_b32 s72, v254, 8
	v_readlane_b32 s73, v254, 9
	v_readlane_b32 s74, v254, 10
	v_readlane_b32 s75, v254, 11
	v_readlane_b32 s76, v254, 12
	v_readlane_b32 s77, v254, 13
	v_readlane_b32 s78, v254, 14
	v_readlane_b32 s79, v254, 15
	v_readlane_b32 s80, v254, 16
	v_readlane_b32 s81, v254, 17
	v_readlane_b32 s82, v254, 18
	v_readlane_b32 s83, v254, 19
	v_readlane_b32 s84, v254, 20
	v_readlane_b32 s85, v254, 21
	v_readlane_b32 s86, v254, 22
	v_readlane_b32 s87, v254, 23
	v_readlane_b32 s88, v254, 24
	v_readlane_b32 s89, v254, 25
	v_readlane_b32 s90, v254, 26
	v_readlane_b32 s91, v254, 27
	v_readlane_b32 s92, v254, 28
	v_readlane_b32 s93, v254, 29
	v_readlane_b32 s94, v254, 30
	v_readlane_b32 s95, v254, 31
	s_nop 4
	s_add_u32 s4, s4, 0x1f80
	s_addc_u32 s5, s5, 0
	v_readfirstlane_b32 s8, v163
	v_lshl_add_u64 v[146:147], s[4:5], 0, v[184:185]
	s_mov_b32 m0, s8
	v_lshl_add_u64 v[128:129], s[4:5], 0, v[128:129]
	v_readfirstlane_b32 s4, v164
	ds_read_b128 v[130:133], v162
	ds_read_b128 v[134:137], v162 offset:1024
	ds_read_b128 v[154:157], v162 offset:2048
	ds_read_b128 v[166:169], v162 offset:3072
	ds_read_b128 v[170:173], v144
	ds_read_b128 v[174:177], v144 offset:1024
	ds_read_b128 v[178:181], v141
	ds_read_b128 v[186:189], v141 offset:1024
	ds_read_b128 v[190:193], v140
	ds_read_b128 v[194:197], v140 offset:1024
	ds_read_b128 v[198:201], v139
	ds_read_b128 v[202:205], v139 offset:1024
	global_load_lds_dwordx4 v[146:147], off
	s_mov_b32 m0, s4
	s_nop 0
	global_load_lds_dwordx4 v[128:129], off
	s_barrier
	s_waitcnt lgkmcnt(0)
	s_waitcnt lgkmcnt(0)
	v_mfma_f32_16x16x32_bf16 v[124:127], v[130:133], v[170:173], v[124:127]
	v_mfma_f32_16x16x32_bf16 v[120:123], v[154:157], v[170:173], v[120:123]
	v_mfma_f32_16x16x32_bf16 v[116:119], v[130:133], v[178:181], v[116:119]
	v_mfma_f32_16x16x32_bf16 v[108:111], v[130:133], v[190:193], v[108:111]
	v_mfma_f32_16x16x32_bf16 v[104:107], v[154:157], v[190:193], v[104:107]
	v_mfma_f32_16x16x32_bf16 v[124:127], v[134:137], v[174:177], v[124:127]
	v_mfma_f32_16x16x32_bf16 v[120:123], v[166:169], v[174:177], v[120:123]
	v_mfma_f32_16x16x32_bf16 v[116:119], v[134:137], v[186:189], v[116:119]
	v_mfma_f32_16x16x32_bf16 v[112:115], v[154:157], v[178:181], v[112:115]
	v_mfma_f32_16x16x32_bf16 v[108:111], v[134:137], v[194:197], v[108:111]
	v_mfma_f32_16x16x32_bf16 v[104:107], v[166:169], v[194:197], v[104:107]
	v_mfma_f32_16x16x32_bf16 v[100:103], v[130:133], v[198:201], v[100:103]
	v_mfma_f32_16x16x32_bf16 v[96:99], v[154:157], v[198:201], v[96:99]
	v_mfma_f32_16x16x32_bf16 v[162:165], v[166:169], v[186:189], v[112:115]
	v_mfma_f32_16x16x32_bf16 v[206:209], v[134:137], v[202:205], v[100:103]
	v_mfma_f32_16x16x32_bf16 v[210:213], v[166:169], v[202:205], v[96:99]
	s_barrier
; #define WAIT_V(n) asm volatile("s_waitcnt vmcnt(" #n ")" ::: "memory")
; #define WAIT_L(n) asm volatile("s_waitcnt lgkmcnt(" #n ")" ::: "memory")
; #define BAR __builtin_amdgcn_s_barrier()
;     ...
;     LDB(B1, 0, 1); BAR; WAIT_L(0); MMA(0, 1, At, B1); BAR;
;     LDA(At, 0, 1); WAIT_V(4); BAR; WAIT_L(0); MMA(1, 0, At, B0); MMA(1, 1, At, B1); BAR; }
;   { LDB(B0, 1, 0); LDA(At, 1, 0); WAIT_V(2); BAR; WAIT_L(0); MMA(0, 0, At, B0); BAR;
	s_nop 2
	ds_read_b128 v[96:99], v161
	ds_read_b128 v[100:103], v161 offset:1024
	ds_read_b128 v[112:115], v161 offset:2048
	ds_read_b128 v[158:161], v161 offset:3072
	s_barrier
	s_waitcnt lgkmcnt(0)
	s_waitcnt lgkmcnt(0)
	v_mfma_f32_16x16x32_bf16 v[92:95], v[96:99], v[170:173], v[92:95]
	v_mfma_f32_16x16x32_bf16 v[88:91], v[112:115], v[170:173], v[88:91]
	v_mfma_f32_16x16x32_bf16 v[84:87], v[96:99], v[178:181], v[84:87]
	v_mfma_f32_16x16x32_bf16 v[76:79], v[96:99], v[190:193], v[76:79]
	v_mfma_f32_16x16x32_bf16 v[72:75], v[112:115], v[190:193], v[72:75]
	v_mfma_f32_16x16x32_bf16 v[92:95], v[100:103], v[174:177], v[92:95]
	v_mfma_f32_16x16x32_bf16 v[88:91], v[158:161], v[174:177], v[88:91]
	v_mfma_f32_16x16x32_bf16 v[84:87], v[100:103], v[186:189], v[84:87]
	v_mfma_f32_16x16x32_bf16 v[80:83], v[112:115], v[178:181], v[80:83]
	v_mfma_f32_16x16x32_bf16 v[76:79], v[100:103], v[194:197], v[76:79]
	v_mfma_f32_16x16x32_bf16 v[72:75], v[158:161], v[194:197], v[72:75]
	v_mfma_f32_16x16x32_bf16 v[68:71], v[96:99], v[198:201], v[68:71]
	v_mfma_f32_16x16x32_bf16 v[64:67], v[112:115], v[198:201], v[64:67]
	v_mfma_f32_16x16x32_bf16 v[170:173], v[158:161], v[186:189], v[80:83]
	v_mfma_f32_16x16x32_bf16 v[174:177], v[100:103], v[202:205], v[68:71]
	v_mfma_f32_16x16x32_bf16 v[178:181], v[158:161], v[202:205], v[64:67]
	s_barrier
	s_nop 2
	ds_read_b128 v[64:67], v144 offset:16384
	ds_read_b128 v[68:71], v144 offset:17408
	ds_read_b128 v[80:83], v141 offset:16384
	ds_read_b128 v[186:189], v141 offset:17408
	ds_read_b128 v[190:193], v140 offset:16384
	ds_read_b128 v[194:197], v140 offset:17408
	ds_read_b128 v[198:201], v139 offset:16384
	ds_read_b128 v[202:205], v139 offset:17408
	s_waitcnt vmcnt(4)
	s_barrier
	s_waitcnt lgkmcnt(0)
	s_waitcnt lgkmcnt(0)
	v_mfma_f32_16x16x32_bf16 v[60:63], v[130:133], v[64:67], v[60:63]
	v_mfma_f32_16x16x32_bf16 v[56:59], v[154:157], v[64:67], v[56:59]
	v_mfma_f32_16x16x32_bf16 v[52:55], v[130:133], v[80:83], v[52:55]
	v_mfma_f32_16x16x32_bf16 v[44:47], v[130:133], v[190:193], v[44:47]
	v_mfma_f32_16x16x32_bf16 v[40:43], v[154:157], v[190:193], v[40:43]
	v_mfma_f32_16x16x32_bf16 v[60:63], v[134:137], v[68:71], v[60:63]
	v_mfma_f32_16x16x32_bf16 v[56:59], v[166:169], v[68:71], v[56:59]
	v_mfma_f32_16x16x32_bf16 v[52:55], v[134:137], v[186:189], v[52:55]
	v_mfma_f32_16x16x32_bf16 v[48:51], v[154:157], v[80:83], v[48:51]
	v_mfma_f32_16x16x32_bf16 v[44:47], v[134:137], v[194:197], v[44:47]
	v_mfma_f32_16x16x32_bf16 v[40:43], v[166:169], v[194:197], v[40:43]
	v_mfma_f32_16x16x32_bf16 v[36:39], v[130:133], v[198:201], v[36:39]
	v_mfma_f32_16x16x32_bf16 v[32:35], v[154:157], v[198:201], v[32:35]
	v_mfma_f32_16x16x32_bf16 v[214:217], v[166:169], v[186:189], v[48:51]
	v_mfma_f32_16x16x32_bf16 v[128:131], v[134:137], v[202:205], v[36:39]
	v_mfma_f32_16x16x32_bf16 v[132:135], v[166:169], v[202:205], v[32:35]
	v_mfma_f32_16x16x32_bf16 v[28:31], v[96:99], v[64:67], v[28:31]
	v_mfma_f32_16x16x32_bf16 v[24:27], v[112:115], v[64:67], v[24:27]
	v_mfma_f32_16x16x32_bf16 v[20:23], v[96:99], v[80:83], v[20:23]
	v_mfma_f32_16x16x32_bf16 v[12:15], v[96:99], v[190:193], v[12:15]
	v_mfma_f32_16x16x32_bf16 v[8:11], v[112:115], v[190:193], v[8:11]
	v_mfma_f32_16x16x32_bf16 v[28:31], v[100:103], v[68:71], v[28:31]
	v_mfma_f32_16x16x32_bf16 v[24:27], v[158:161], v[68:71], v[24:27]
	v_mfma_f32_16x16x32_bf16 v[20:23], v[100:103], v[186:189], v[20:23]
	v_mfma_f32_16x16x32_bf16 v[16:19], v[112:115], v[80:83], v[16:19]
	v_mfma_f32_16x16x32_bf16 v[12:15], v[100:103], v[194:197], v[12:15]
	v_mfma_f32_16x16x32_bf16 v[8:11], v[158:161], v[194:197], v[8:11]
	v_mfma_f32_16x16x32_bf16 v[4:7], v[96:99], v[198:201], v[4:7]
	v_mfma_f32_16x16x32_bf16 v[0:3], v[112:115], v[198:201], v[0:3]
	v_mfma_f32_16x16x32_bf16 v[154:157], v[158:161], v[186:189], v[16:19]
	v_mfma_f32_16x16x32_bf16 v[166:169], v[100:103], v[202:205], v[4:7]
	v_mfma_f32_16x16x32_bf16 v[158:161], v[158:161], v[202:205], v[0:3]
	s_barrier
	s_nop 2
	ds_read_b128 v[0:3], v152
	ds_read_b128 v[4:7], v152 offset:1024
	ds_read_b128 v[16:19], v152 offset:2048
	ds_read_b128 v[150:153], v152 offset:3072
	ds_read_b128 v[32:35], v144 offset:32768
	ds_read_b128 v[36:39], v144 offset:33792
	ds_read_b128 v[48:51], v141 offset:32768
	ds_read_b128 v[68:71], v141 offset:33792
	ds_read_b128 v[186:189], v140 offset:32768
	ds_read_b128 v[190:193], v140 offset:33792
	ds_read_b128 v[194:197], v139 offset:32768
	ds_read_b128 v[198:201], v139 offset:33792
	s_waitcnt vmcnt(2)
	s_barrier
; #define WAIT_V(n) asm volatile("s_waitcnt vmcnt(" #n ")" ::: "memory")
; #define WAIT_L(n) asm volatile("s_waitcnt lgkmcnt(" #n ")" ::: "memory")
; #define BAR __builtin_amdgcn_s_barrier()
;     ...
;   { LDB(B0, 1, 0); LDA(At, 1, 0); WAIT_V(2); BAR; WAIT_L(0); MMA(0, 0, At, B0); BAR;
;     LDB(B1, 1, 1); WAIT_V(0); BAR; WAIT_L(0); MMA(0, 1, At, B1); BAR;
;     LDA(At, 1, 1); BAR; WAIT_L(0); MMA(1, 0, At, B0); MMA(1, 1, At, B1); BAR; }
;   if (wr == 0) BAR;
	s_waitcnt lgkmcnt(0)
	s_waitcnt lgkmcnt(0)
	v_mfma_f32_16x16x32_bf16 v[64:67], v[0:3], v[32:35], v[124:127]
	v_mfma_f32_16x16x32_bf16 v[112:115], v[4:7], v[36:39], v[64:67]
	v_mfma_f32_16x16x32_bf16 v[64:67], v[16:19], v[32:35], v[120:123]
	v_mfma_f32_16x16x32_bf16 v[96:99], v[150:153], v[36:39], v[64:67]
	v_mfma_f32_16x16x32_bf16 v[64:67], v[0:3], v[48:51], v[116:119]
	v_mfma_f32_16x16x32_bf16 v[116:119], v[4:7], v[68:71], v[64:67]
	v_mfma_f32_16x16x32_bf16 v[64:67], v[16:19], v[48:51], v[162:165]
	v_mfma_f32_16x16x32_bf16 v[100:103], v[150:153], v[68:71], v[64:67]
	v_mfma_f32_16x16x32_bf16 v[64:67], v[0:3], v[186:189], v[108:111]
	v_mfma_f32_16x16x32_bf16 v[120:123], v[4:7], v[190:193], v[64:67]
	v_mfma_f32_16x16x32_bf16 v[64:67], v[16:19], v[186:189], v[104:107]
	v_mfma_f32_16x16x32_bf16 v[104:107], v[150:153], v[190:193], v[64:67]
	v_mfma_f32_16x16x32_bf16 v[64:67], v[0:3], v[194:197], v[206:209]
	v_mfma_f32_16x16x32_bf16 v[124:127], v[4:7], v[198:201], v[64:67]
	v_mfma_f32_16x16x32_bf16 v[64:67], v[16:19], v[194:197], v[210:213]
	v_mfma_f32_16x16x32_bf16 v[108:111], v[150:153], v[198:201], v[64:67]
	s_barrier
	ds_read_b128 v[162:165], v148
	ds_read_b128 v[202:205], v148 offset:1024
	ds_read_b128 v[206:209], v148 offset:2048
	ds_read_b128 v[146:149], v148 offset:3072
	s_waitcnt vmcnt(0)
	s_barrier
	s_waitcnt lgkmcnt(0)
	s_waitcnt lgkmcnt(0)
	v_mfma_f32_16x16x32_bf16 v[64:67], v[162:165], v[32:35], v[92:95]
	v_mfma_f32_16x16x32_bf16 v[32:35], v[206:209], v[32:35], v[88:91]
	v_mfma_f32_16x16x32_bf16 v[80:83], v[202:205], v[36:39], v[64:67]
	v_mfma_f32_16x16x32_bf16 v[64:67], v[146:149], v[36:39], v[32:35]
	v_mfma_f32_16x16x32_bf16 v[32:35], v[162:165], v[48:51], v[84:87]
	v_mfma_f32_16x16x32_bf16 v[84:87], v[202:205], v[68:71], v[32:35]
	v_mfma_f32_16x16x32_bf16 v[32:35], v[206:209], v[48:51], v[170:173]
	v_mfma_f32_16x16x32_bf16 v[68:71], v[146:149], v[68:71], v[32:35]
	v_mfma_f32_16x16x32_bf16 v[32:35], v[162:165], v[186:189], v[76:79]
	v_mfma_f32_16x16x32_bf16 v[88:91], v[202:205], v[190:193], v[32:35]
	v_mfma_f32_16x16x32_bf16 v[32:35], v[206:209], v[186:189], v[72:75]
	v_mfma_f32_16x16x32_bf16 v[72:75], v[146:149], v[190:193], v[32:35]
	v_mfma_f32_16x16x32_bf16 v[32:35], v[162:165], v[194:197], v[174:177]
	v_mfma_f32_16x16x32_bf16 v[92:95], v[202:205], v[198:201], v[32:35]
	v_mfma_f32_16x16x32_bf16 v[32:35], v[206:209], v[194:197], v[178:181]
	v_mfma_f32_16x16x32_bf16 v[76:79], v[146:149], v[198:201], v[32:35]
	s_barrier
	ds_read_b128 v[170:173], v144 offset:49152
	ds_read_b128 v[174:177], v144 offset:50176
	ds_read_b128 v[178:181], v141 offset:49152
	ds_read_b128 v[186:189], v141 offset:50176
	ds_read_b128 v[190:193], v140 offset:49152
	ds_read_b128 v[194:197], v140 offset:50176
	ds_read_b128 v[198:201], v139 offset:49152
	ds_read_b128 v[210:213], v139 offset:50176
	s_barrier
	s_waitcnt lgkmcnt(0)
	s_waitcnt lgkmcnt(0)
	v_mfma_f32_16x16x32_bf16 v[32:35], v[0:3], v[170:173], v[60:63]
	v_mfma_f32_16x16x32_bf16 v[36:39], v[0:3], v[178:181], v[52:55]
	v_mfma_f32_16x16x32_bf16 v[44:47], v[0:3], v[190:193], v[44:47]
	v_mfma_f32_16x16x32_bf16 v[0:3], v[0:3], v[198:201], v[128:131]
	v_mfma_f32_16x16x32_bf16 v[48:51], v[4:7], v[174:177], v[32:35]
	v_mfma_f32_16x16x32_bf16 v[32:35], v[16:19], v[170:173], v[56:59]
	v_mfma_f32_16x16x32_bf16 v[52:55], v[4:7], v[186:189], v[36:39]
	v_mfma_f32_16x16x32_bf16 v[36:39], v[16:19], v[178:181], v[214:217]
	v_mfma_f32_16x16x32_bf16 v[40:43], v[16:19], v[190:193], v[40:43]
	v_mfma_f32_16x16x32_bf16 v[60:63], v[4:7], v[210:213], v[0:3]
	v_mfma_f32_16x16x32_bf16 v[0:3], v[16:19], v[198:201], v[132:135]
	v_mfma_f32_16x16x32_bf16 v[32:35], v[150:153], v[174:177], v[32:35]
	v_mfma_f32_16x16x32_bf16 v[36:39], v[150:153], v[186:189], v[36:39]
	v_mfma_f32_16x16x32_bf16 v[56:59], v[4:7], v[194:197], v[44:47]
	v_mfma_f32_16x16x32_bf16 v[40:43], v[150:153], v[194:197], v[40:43]
	v_mfma_f32_16x16x32_bf16 v[44:47], v[150:153], v[210:213], v[0:3]
	v_mfma_f32_16x16x32_bf16 v[0:3], v[162:165], v[170:173], v[28:31]
	v_mfma_f32_16x16x32_bf16 v[12:15], v[162:165], v[190:193], v[12:15]
	v_mfma_f32_16x16x32_bf16 v[16:19], v[202:205], v[174:177], v[0:3]
	v_mfma_f32_16x16x32_bf16 v[0:3], v[206:209], v[170:173], v[24:27]
	v_mfma_f32_16x16x32_bf16 v[4:7], v[162:165], v[178:181], v[20:23]
	v_mfma_f32_16x16x32_bf16 v[24:27], v[202:205], v[194:197], v[12:15]
	v_mfma_f32_16x16x32_bf16 v[12:15], v[162:165], v[198:201], v[166:169]
	v_mfma_f32_16x16x32_bf16 v[20:23], v[202:205], v[186:189], v[4:7]
	v_mfma_f32_16x16x32_bf16 v[4:7], v[206:209], v[178:181], v[154:157]
	v_mfma_f32_16x16x32_bf16 v[8:11], v[206:209], v[190:193], v[8:11]
	v_mfma_f32_16x16x32_bf16 v[28:31], v[202:205], v[210:213], v[12:15]
	v_mfma_f32_16x16x32_bf16 v[12:15], v[206:209], v[198:201], v[158:161]
	v_mfma_f32_16x16x32_bf16 v[0:3], v[146:149], v[174:177], v[0:3]
	v_mfma_f32_16x16x32_bf16 v[4:7], v[146:149], v[186:189], v[4:7]
	v_mfma_f32_16x16x32_bf16 v[8:11], v[146:149], v[194:197], v[8:11]
	v_mfma_f32_16x16x32_bf16 v[12:15], v[146:149], v[210:213], v[12:15]
	v_cmp_gt_u32_e32 vcc, s57, v143
	s_barrier
	s_and_saveexec_b64 s[4:5], vcc
	s_cbranch_execz .LBB0_72
	s_barrier

; #define WAIT_V(n) asm volatile("s_waitcnt vmcnt(" #n ")" ::: "memory")
; #define WAIT_L(n) asm volatile("s_waitcnt lgkmcnt(" #n ")" ::: "memory")
; #define BAR __builtin_amdgcn_s_barrier()
; #define SCHED __builtin_amdgcn_sched_barrier(0)
;     ...
;     LDB(B0, 0, 0); SCHED; LDA(At, 0, 0); STAGE(SA(1, 1), A, brow + HALF, t + 1);
;     WAIT_L(8); BAR; WAIT_L(0); MMA(0, 0, At, B0); BAR; SCHED;
;     LDB(B1, 0, 1); STAGE(SB(0, 0), Bt, bcol, t + 2);
;     BAR; WAIT_L(0); MMA(0, 1, At, B1); BAR;
;     LDA(At, 0, 1); STAGE(SA(0, 0), A, brow, t + 2);
;     BAR; WAIT_L(0); MMA(1, 0, At, B0); BAR; SCHED;
;     STAGE(SB(0, 1), Bt, bcol1, t + 2);
;     WAIT_V(6); BAR; MMA(1, 1, At, B1); BAR;
.LBB0_1142:
	ds_read_b128 v[172:175], v169
	ds_read_b128 v[176:179], v169 offset:1024
	ds_read_b128 v[180:183], v169 offset:2048
	ds_read_b128 v[184:187], v169 offset:3072
	v_add_u32_e32 v170, 0xc000, v154
	v_add_u32_e32 v171, 0xe000, v154
	s_add_u32 m0, s27, 0xc000
	ds_read_b128 v[188:191], v147
	ds_read_b128 v[192:195], v147 offset:1024
	ds_read_b128 v[196:199], v146
	ds_read_b128 v[200:203], v146 offset:1024
	ds_read_b128 v[204:207], v145
	ds_read_b128 v[208:211], v145 offset:1024
	ds_read_b128 v[212:215], v144
	ds_read_b128 v[216:219], v144 offset:1024
	global_load_lds_dwordx4 v158, s[64:65]
	s_add_u32 s64, s64, 0x100
	s_addc_u32 s65, s65, 0
	s_add_u32 m0, s27, 0xe000
	s_nop 0
	global_load_lds_dwordx4 v159, s[66:67]
	s_add_u32 s66, s66, 0x100
	s_addc_u32 s67, s67, 0
	s_waitcnt lgkmcnt(8)
	s_barrier
	s_waitcnt lgkmcnt(0)
	v_mfma_f32_16x16x32_bf16 v[124:127], v[172:175], v[188:191], v[124:127]
	v_mfma_f32_16x16x32_bf16 v[120:123], v[180:183], v[188:191], v[120:123]
	v_mfma_f32_16x16x32_bf16 v[116:119], v[172:175], v[196:199], v[116:119]
	v_mfma_f32_16x16x32_bf16 v[112:115], v[180:183], v[196:199], v[112:115]
	v_mfma_f32_16x16x32_bf16 v[108:111], v[172:175], v[204:207], v[108:111]
	v_mfma_f32_16x16x32_bf16 v[104:107], v[180:183], v[204:207], v[104:107]
	v_mfma_f32_16x16x32_bf16 v[100:103], v[172:175], v[212:215], v[100:103]
	v_mfma_f32_16x16x32_bf16 v[96:99], v[180:183], v[212:215], v[96:99]
	v_mfma_f32_16x16x32_bf16 v[124:127], v[176:179], v[192:195], v[124:127]
	v_mfma_f32_16x16x32_bf16 v[120:123], v[184:187], v[192:195], v[120:123]
	v_mfma_f32_16x16x32_bf16 v[116:119], v[176:179], v[200:203], v[116:119]
	v_mfma_f32_16x16x32_bf16 v[112:115], v[184:187], v[200:203], v[112:115]
	v_mfma_f32_16x16x32_bf16 v[108:111], v[176:179], v[208:211], v[108:111]
	v_mfma_f32_16x16x32_bf16 v[104:107], v[184:187], v[208:211], v[104:107]
	v_mfma_f32_16x16x32_bf16 v[100:103], v[176:179], v[216:219], v[100:103]
	v_mfma_f32_16x16x32_bf16 v[96:99], v[184:187], v[216:219], v[96:99]
	s_barrier
	s_add_u32 m0, s27, s36
	ds_read_b128 v[220:223], v168
	ds_read_b128 v[224:227], v168 offset:1024
	ds_read_b128 v[228:231], v168 offset:2048
	ds_read_b128 v[232:235], v168 offset:3072
	global_load_lds_dwordx4 v156, s[68:69]
	s_add_u32 s68, s68, 0x100
	s_addc_u32 s69, s69, 0
	s_add_u32 m0, s27, 0x2000
	s_add_u32 m0, m0, s36
	s_nop 0
	global_load_lds_dwordx4 v157, s[70:71]
	s_add_u32 s70, s70, 0x100
	s_addc_u32 s71, s71, 0
	s_barrier
	s_waitcnt lgkmcnt(0)
	v_mfma_f32_16x16x32_bf16 v[92:95], v[220:223], v[188:191], v[92:95]
	v_mfma_f32_16x16x32_bf16 v[88:91], v[228:231], v[188:191], v[88:91]
	v_mfma_f32_16x16x32_bf16 v[84:87], v[220:223], v[196:199], v[84:87]
	v_mfma_f32_16x16x32_bf16 v[80:83], v[228:231], v[196:199], v[80:83]
	v_mfma_f32_16x16x32_bf16 v[76:79], v[220:223], v[204:207], v[76:79]
	v_mfma_f32_16x16x32_bf16 v[72:75], v[228:231], v[204:207], v[72:75]
	v_mfma_f32_16x16x32_bf16 v[68:71], v[220:223], v[212:215], v[68:71]
	v_mfma_f32_16x16x32_bf16 v[64:67], v[228:231], v[212:215], v[64:67]
	v_mfma_f32_16x16x32_bf16 v[92:95], v[224:227], v[192:195], v[92:95]
	v_mfma_f32_16x16x32_bf16 v[88:91], v[232:235], v[192:195], v[88:91]
	v_mfma_f32_16x16x32_bf16 v[84:87], v[224:227], v[200:203], v[84:87]
	v_mfma_f32_16x16x32_bf16 v[80:83], v[232:235], v[200:203], v[80:83]
	v_mfma_f32_16x16x32_bf16 v[76:79], v[224:227], v[208:211], v[76:79]
	v_mfma_f32_16x16x32_bf16 v[72:75], v[232:235], v[208:211], v[72:75]
	v_mfma_f32_16x16x32_bf16 v[68:71], v[224:227], v[216:219], v[68:71]
	v_mfma_f32_16x16x32_bf16 v[64:67], v[232:235], v[216:219], v[64:67]
	s_mov_b32 m0, s27
	s_barrier
	ds_read_b128 v[188:191], v147 offset:16384
	ds_read_b128 v[192:195], v147 offset:17408
	ds_read_b128 v[196:199], v146 offset:16384
	ds_read_b128 v[200:203], v146 offset:17408
	ds_read_b128 v[204:207], v145 offset:16384
	ds_read_b128 v[208:211], v145 offset:17408
	ds_read_b128 v[212:215], v144 offset:16384
	ds_read_b128 v[216:219], v144 offset:17408
	global_load_lds_dwordx4 v158, s[72:73]
	s_add_u32 s72, s72, 0x100
	s_addc_u32 s73, s73, 0
	s_add_u32 m0, s27, 0x2000
	s_nop 0
	global_load_lds_dwordx4 v159, s[74:75]
	s_add_u32 s74, s74, 0x100
	s_addc_u32 s75, s75, 0
	s_barrier
	s_waitcnt lgkmcnt(0)
	v_mfma_f32_16x16x32_bf16 v[60:63], v[172:175], v[188:191], v[60:63]
	v_mfma_f32_16x16x32_bf16 v[56:59], v[180:183], v[188:191], v[56:59]
	v_mfma_f32_16x16x32_bf16 v[52:55], v[172:175], v[196:199], v[52:55]
	v_mfma_f32_16x16x32_bf16 v[48:51], v[180:183], v[196:199], v[48:51]
	v_mfma_f32_16x16x32_bf16 v[44:47], v[172:175], v[204:207], v[44:47]
	v_mfma_f32_16x16x32_bf16 v[40:43], v[180:183], v[204:207], v[40:43]
	v_mfma_f32_16x16x32_bf16 v[36:39], v[172:175], v[212:215], v[36:39]
	v_mfma_f32_16x16x32_bf16 v[32:35], v[180:183], v[212:215], v[32:35]
	v_mfma_f32_16x16x32_bf16 v[60:63], v[176:179], v[192:195], v[60:63]
	v_mfma_f32_16x16x32_bf16 v[56:59], v[184:187], v[192:195], v[56:59]
	v_mfma_f32_16x16x32_bf16 v[52:55], v[176:179], v[200:203], v[52:55]
	v_mfma_f32_16x16x32_bf16 v[48:51], v[184:187], v[200:203], v[48:51]
	v_mfma_f32_16x16x32_bf16 v[44:47], v[176:179], v[208:211], v[44:47]
	v_mfma_f32_16x16x32_bf16 v[40:43], v[184:187], v[208:211], v[40:43]
	v_mfma_f32_16x16x32_bf16 v[36:39], v[176:179], v[216:219], v[36:39]
	v_mfma_f32_16x16x32_bf16 v[32:35], v[184:187], v[216:219], v[32:35]
	s_barrier
	s_add_u32 m0, s27, s37
	s_nop 0
	global_load_lds_dwordx4 v156, s[76:77]
	s_add_u32 s76, s76, 0x100
	s_addc_u32 s77, s77, 0
	s_add_u32 m0, s27, 0x2000
	s_add_u32 m0, m0, s37
	s_nop 0
	global_load_lds_dwordx4 v157, s[78:79]
	s_add_u32 s78, s78, 0x100
	s_addc_u32 s79, s79, 0
	s_waitcnt vmcnt(6)
	s_barrier
; #define WAIT_V(n) asm volatile("s_waitcnt vmcnt(" #n ")" ::: "memory")
; #define WAIT_L(n) asm volatile("s_waitcnt lgkmcnt(" #n ")" ::: "memory")
; #define BAR __builtin_amdgcn_s_barrier()
; #define SCHED __builtin_amdgcn_sched_barrier(0)
;     ...
;     WAIT_V(6); BAR; MMA(1, 1, At, B1); BAR;
;     LDB(B0, 1, 0); SCHED; LDA(At, 1, 0); STAGE(SA(0, 1), A, brow + HALF, t + 2);
;     WAIT_L(8); BAR; WAIT_L(0); MMA(0, 0, At, B0); BAR; SCHED;
;     LDB(B1, 1, 1); STAGE(SB(1, 0), Bt, bcol, t + 3);
;     BAR; WAIT_L(0); MMA(0, 1, At, B1); BAR;
;     LDA(At, 1, 1); STAGE(SA(1, 0), A, brow, t + 3);
	v_mfma_f32_16x16x32_bf16 v[28:31], v[220:223], v[188:191], v[28:31]
	v_mfma_f32_16x16x32_bf16 v[24:27], v[228:231], v[188:191], v[24:27]
	v_mfma_f32_16x16x32_bf16 v[20:23], v[220:223], v[196:199], v[20:23]
	v_mfma_f32_16x16x32_bf16 v[16:19], v[228:231], v[196:199], v[16:19]
	v_mfma_f32_16x16x32_bf16 v[12:15], v[220:223], v[204:207], v[12:15]
	v_mfma_f32_16x16x32_bf16 v[8:11], v[228:231], v[204:207], v[8:11]
	v_mfma_f32_16x16x32_bf16 v[4:7], v[220:223], v[212:215], v[4:7]
	v_mfma_f32_16x16x32_bf16 v[0:3], v[228:231], v[212:215], v[0:3]
	v_mfma_f32_16x16x32_bf16 v[28:31], v[224:227], v[192:195], v[28:31]
	v_mfma_f32_16x16x32_bf16 v[24:27], v[232:235], v[192:195], v[24:27]
	v_mfma_f32_16x16x32_bf16 v[20:23], v[224:227], v[200:203], v[20:23]
	v_mfma_f32_16x16x32_bf16 v[16:19], v[232:235], v[200:203], v[16:19]
	v_mfma_f32_16x16x32_bf16 v[12:15], v[224:227], v[208:211], v[12:15]
	v_mfma_f32_16x16x32_bf16 v[8:11], v[232:235], v[208:211], v[8:11]
	v_mfma_f32_16x16x32_bf16 v[4:7], v[224:227], v[216:219], v[4:7]
	v_mfma_f32_16x16x32_bf16 v[0:3], v[232:235], v[216:219], v[0:3]
	s_barrier
	ds_read_b128 v[172:175], v160
	ds_read_b128 v[176:179], v160 offset:1024
	ds_read_b128 v[180:183], v160 offset:2048
	ds_read_b128 v[184:187], v160 offset:3072
	s_add_u32 m0, s27, 0x4000
	ds_read_b128 v[188:191], v147 offset:32768
	ds_read_b128 v[192:195], v147 offset:33792
	ds_read_b128 v[196:199], v146 offset:32768
	ds_read_b128 v[200:203], v146 offset:33792
	ds_read_b128 v[204:207], v145 offset:32768
	ds_read_b128 v[208:211], v145 offset:33792
	ds_read_b128 v[212:215], v144 offset:32768
	ds_read_b128 v[216:219], v144 offset:33792
	global_load_lds_dwordx4 v158, s[80:81]
	s_add_u32 s80, s80, 0x100
	s_addc_u32 s81, s81, 0
	s_add_u32 m0, s27, 0x6000
	s_nop 0
	global_load_lds_dwordx4 v159, s[82:83]
	s_add_u32 s82, s82, 0x100
	s_addc_u32 s83, s83, 0
	s_waitcnt lgkmcnt(8)
	s_barrier
	s_waitcnt lgkmcnt(0)
	v_mfma_f32_16x16x32_bf16 v[124:127], v[172:175], v[188:191], v[124:127]
	v_mfma_f32_16x16x32_bf16 v[120:123], v[180:183], v[188:191], v[120:123]
	v_mfma_f32_16x16x32_bf16 v[116:119], v[172:175], v[196:199], v[116:119]
	v_mfma_f32_16x16x32_bf16 v[112:115], v[180:183], v[196:199], v[112:115]
	v_mfma_f32_16x16x32_bf16 v[108:111], v[172:175], v[204:207], v[108:111]
	v_mfma_f32_16x16x32_bf16 v[104:107], v[180:183], v[204:207], v[104:107]
	v_mfma_f32_16x16x32_bf16 v[100:103], v[172:175], v[212:215], v[100:103]
	v_mfma_f32_16x16x32_bf16 v[96:99], v[180:183], v[212:215], v[96:99]
	v_mfma_f32_16x16x32_bf16 v[124:127], v[176:179], v[192:195], v[124:127]
	v_mfma_f32_16x16x32_bf16 v[120:123], v[184:187], v[192:195], v[120:123]
	v_mfma_f32_16x16x32_bf16 v[116:119], v[176:179], v[200:203], v[116:119]
	v_mfma_f32_16x16x32_bf16 v[112:115], v[184:187], v[200:203], v[112:115]
	v_mfma_f32_16x16x32_bf16 v[108:111], v[176:179], v[208:211], v[108:111]
	v_mfma_f32_16x16x32_bf16 v[104:107], v[184:187], v[208:211], v[104:107]
	v_mfma_f32_16x16x32_bf16 v[100:103], v[176:179], v[216:219], v[100:103]
	v_mfma_f32_16x16x32_bf16 v[96:99], v[184:187], v[216:219], v[96:99]
	s_barrier
	s_add_u32 m0, s27, s38
	ds_read_b128 v[220:223], v155
	ds_read_b128 v[224:227], v155 offset:1024
	ds_read_b128 v[228:231], v155 offset:2048
	ds_read_b128 v[232:235], v155 offset:3072
	global_load_lds_dwordx4 v156, s[84:85]
	s_add_u32 s84, s84, 0x100
	s_addc_u32 s85, s85, 0
	s_add_u32 m0, s27, 0x2000
	s_add_u32 m0, m0, s38
	s_nop 0
	global_load_lds_dwordx4 v157, s[86:87]
	s_add_u32 s86, s86, 0x100
	s_addc_u32 s87, s87, 0
	s_barrier
	s_waitcnt lgkmcnt(0)
	v_mfma_f32_16x16x32_bf16 v[92:95], v[220:223], v[188:191], v[92:95]
	v_mfma_f32_16x16x32_bf16 v[88:91], v[228:231], v[188:191], v[88:91]
	v_mfma_f32_16x16x32_bf16 v[84:87], v[220:223], v[196:199], v[84:87]
	v_mfma_f32_16x16x32_bf16 v[80:83], v[228:231], v[196:199], v[80:83]
	v_mfma_f32_16x16x32_bf16 v[76:79], v[220:223], v[204:207], v[76:79]
	v_mfma_f32_16x16x32_bf16 v[72:75], v[228:231], v[204:207], v[72:75]
	v_mfma_f32_16x16x32_bf16 v[68:71], v[220:223], v[212:215], v[68:71]
	v_mfma_f32_16x16x32_bf16 v[64:67], v[228:231], v[212:215], v[64:67]
	v_mfma_f32_16x16x32_bf16 v[92:95], v[224:227], v[192:195], v[92:95]
	v_mfma_f32_16x16x32_bf16 v[88:91], v[232:235], v[192:195], v[88:91]
	v_mfma_f32_16x16x32_bf16 v[84:87], v[224:227], v[200:203], v[84:87]
	v_mfma_f32_16x16x32_bf16 v[80:83], v[232:235], v[200:203], v[80:83]
	v_mfma_f32_16x16x32_bf16 v[76:79], v[224:227], v[208:211], v[76:79]
	v_mfma_f32_16x16x32_bf16 v[72:75], v[232:235], v[208:211], v[72:75]
	v_mfma_f32_16x16x32_bf16 v[68:71], v[224:227], v[216:219], v[68:71]
	v_mfma_f32_16x16x32_bf16 v[64:67], v[232:235], v[216:219], v[64:67]
	s_add_u32 m0, s27, 0x8000
	s_barrier
	ds_read_b128 v[188:191], v147 offset:49152
	ds_read_b128 v[192:195], v147 offset:50176
	ds_read_b128 v[196:199], v146 offset:49152
	ds_read_b128 v[200:203], v146 offset:50176
	ds_read_b128 v[204:207], v145 offset:49152
	ds_read_b128 v[208:211], v145 offset:50176
	ds_read_b128 v[212:215], v144 offset:49152
	ds_read_b128 v[216:219], v144 offset:50176
	global_load_lds_dwordx4 v158, s[88:89]
	s_add_u32 s88, s88, 0x100
	s_addc_u32 s89, s89, 0
	s_add_u32 m0, s27, 0xa000
	s_nop 0
	global_load_lds_dwordx4 v159, s[90:91]
	s_add_u32 s90, s90, 0x100
	s_addc_u32 s91, s91, 0
	s_barrier
; #define WAIT_V(n) asm volatile("s_waitcnt vmcnt(" #n ")" ::: "memory")
; #define WAIT_L(n) asm volatile("s_waitcnt lgkmcnt(" #n ")" ::: "memory")
; #define BAR __builtin_amdgcn_s_barrier()
; #define SCHED __builtin_amdgcn_sched_barrier(0)
;     ...
;     BAR; WAIT_L(0); MMA(1, 0, At, B0); BAR; SCHED;
;     STAGE(SB(1, 1), Bt, bcol1, t + 3);
;     WAIT_V(6); BAR; MMA(1, 1, At, B1); BAR;
;   }
;   { LDB(B0, 0, 0); LDA(At, 0, 0); STAGE(SA(1, 1), A, brow + HALF, nt - 1);
;     BAR; WAIT_L(0); MMA(0, 0, At, B0); BAR;
	s_waitcnt lgkmcnt(0)
	v_mfma_f32_16x16x32_bf16 v[60:63], v[172:175], v[188:191], v[60:63]
	v_mfma_f32_16x16x32_bf16 v[56:59], v[180:183], v[188:191], v[56:59]
	v_mfma_f32_16x16x32_bf16 v[52:55], v[172:175], v[196:199], v[52:55]
	v_mfma_f32_16x16x32_bf16 v[48:51], v[180:183], v[196:199], v[48:51]
	v_mfma_f32_16x16x32_bf16 v[44:47], v[172:175], v[204:207], v[44:47]
	v_mfma_f32_16x16x32_bf16 v[40:43], v[180:183], v[204:207], v[40:43]
	v_mfma_f32_16x16x32_bf16 v[36:39], v[172:175], v[212:215], v[36:39]
	v_mfma_f32_16x16x32_bf16 v[32:35], v[180:183], v[212:215], v[32:35]
	v_mfma_f32_16x16x32_bf16 v[60:63], v[176:179], v[192:195], v[60:63]
	v_mfma_f32_16x16x32_bf16 v[56:59], v[184:187], v[192:195], v[56:59]
	v_mfma_f32_16x16x32_bf16 v[52:55], v[176:179], v[200:203], v[52:55]
	v_mfma_f32_16x16x32_bf16 v[48:51], v[184:187], v[200:203], v[48:51]
	v_mfma_f32_16x16x32_bf16 v[44:47], v[176:179], v[208:211], v[44:47]
	v_mfma_f32_16x16x32_bf16 v[40:43], v[184:187], v[208:211], v[40:43]
	v_mfma_f32_16x16x32_bf16 v[36:39], v[176:179], v[216:219], v[36:39]
	v_mfma_f32_16x16x32_bf16 v[32:35], v[184:187], v[216:219], v[32:35]
	s_barrier
	s_add_u32 m0, s27, s39
	s_nop 0
	global_load_lds_dwordx4 v156, s[92:93]
	s_add_u32 s92, s92, 0x100
	s_addc_u32 s93, s93, 0
	s_add_u32 m0, s27, 0x2000
	s_add_u32 m0, m0, s39
	s_nop 0
	global_load_lds_dwordx4 v157, s[94:95]
	s_add_u32 s94, s94, 0x100
	s_addc_u32 s95, s95, 0
	s_waitcnt vmcnt(6)
	s_barrier
	v_mfma_f32_16x16x32_bf16 v[28:31], v[220:223], v[188:191], v[28:31]
	v_mfma_f32_16x16x32_bf16 v[24:27], v[228:231], v[188:191], v[24:27]
	v_mfma_f32_16x16x32_bf16 v[20:23], v[220:223], v[196:199], v[20:23]
	v_mfma_f32_16x16x32_bf16 v[16:19], v[228:231], v[196:199], v[16:19]
	v_mfma_f32_16x16x32_bf16 v[12:15], v[220:223], v[204:207], v[12:15]
	v_mfma_f32_16x16x32_bf16 v[8:11], v[228:231], v[204:207], v[8:11]
	v_mfma_f32_16x16x32_bf16 v[4:7], v[220:223], v[212:215], v[4:7]
	v_mfma_f32_16x16x32_bf16 v[0:3], v[228:231], v[212:215], v[0:3]
	v_mfma_f32_16x16x32_bf16 v[28:31], v[224:227], v[192:195], v[28:31]
	v_mfma_f32_16x16x32_bf16 v[24:27], v[232:235], v[192:195], v[24:27]
	v_mfma_f32_16x16x32_bf16 v[20:23], v[224:227], v[200:203], v[20:23]
	v_mfma_f32_16x16x32_bf16 v[16:19], v[232:235], v[200:203], v[16:19]
	v_mfma_f32_16x16x32_bf16 v[12:15], v[224:227], v[208:211], v[12:15]
	v_mfma_f32_16x16x32_bf16 v[8:11], v[232:235], v[208:211], v[8:11]
	v_mfma_f32_16x16x32_bf16 v[4:7], v[224:227], v[216:219], v[4:7]
	v_mfma_f32_16x16x32_bf16 v[0:3], v[232:235], v[216:219], v[0:3]
	s_add_i32 s25, s25, 2
	s_add_u32 s30, s30, 0x100
	s_addc_u32 s31, s31, 0
	s_cmp_lt_u32 s25, 60
	s_barrier
	s_cbranch_scc1 .LBB0_1142
	v_readlane_b32 s64, v254, 0
	v_readlane_b32 s65, v254, 1
	v_readlane_b32 s66, v254, 2
	v_readlane_b32 s67, v254, 3
	v_readlane_b32 s68, v254, 4
	v_readlane_b32 s69, v254, 5
	v_readlane_b32 s70, v254, 6
	v_readlane_b32 s71, v254, 7
	v_readlane_b32 s72, v254, 8
	v_readlane_b32 s73, v254, 9
	v_readlane_b32 s74, v254, 10
	v_readlane_b32 s75, v254, 11
	v_readlane_b32 s76, v254, 12
	v_readlane_b32 s77, v254, 13
	v_readlane_b32 s78, v254, 14
	v_readlane_b32 s79, v254, 15
	v_readlane_b32 s80, v254, 16
	v_readlane_b32 s81, v254, 17
	v_readlane_b32 s82, v254, 18
	v_readlane_b32 s83, v254, 19
	v_readlane_b32 s84, v254, 20
	v_readlane_b32 s85, v254, 21
	v_readlane_b32 s86, v254, 22
	v_readlane_b32 s87, v254, 23
	v_readlane_b32 s88, v254, 24
	v_readlane_b32 s89, v254, 25
	v_readlane_b32 s90, v254, 26
	v_readlane_b32 s91, v254, 27
	v_readlane_b32 s92, v254, 28
	v_readlane_b32 s93, v254, 29
	v_readlane_b32 s94, v254, 30
	v_readlane_b32 s95, v254, 31
	s_nop 4
	s_add_u32 s28, s28, 0x1f80
	s_addc_u32 s29, s29, 0
	v_readfirstlane_b32 s25, v170
	v_lshl_add_u64 v[134:135], s[28:29], 0, v[136:137]
	s_mov_b32 m0, s25
	v_readfirstlane_b32 s25, v171
	ds_read_b128 v[130:133], v169
	ds_read_b128 v[156:159], v169 offset:1024
	ds_read_b128 v[162:165], v169 offset:2048
	ds_read_b128 v[172:175], v169 offset:3072
	ds_read_b128 v[176:179], v147
	ds_read_b128 v[180:183], v147 offset:1024
	ds_read_b128 v[184:187], v146
	ds_read_b128 v[188:191], v146 offset:1024
	ds_read_b128 v[192:195], v145
	ds_read_b128 v[196:199], v145 offset:1024
	ds_read_b128 v[200:203], v144
	ds_read_b128 v[204:207], v144 offset:1024
	global_load_lds_dwordx4 v[134:135], off
	v_lshl_add_u64 v[128:129], s[28:29], 0, v[128:129]
	s_mov_b32 m0, s25
	s_nop 0
	global_load_lds_dwordx4 v[128:129], off
	s_barrier
	s_waitcnt lgkmcnt(0)
	s_waitcnt lgkmcnt(0)
	v_mfma_f32_16x16x32_bf16 v[124:127], v[130:133], v[176:179], v[124:127]
	v_mfma_f32_16x16x32_bf16 v[120:123], v[162:165], v[176:179], v[120:123]
	v_mfma_f32_16x16x32_bf16 v[116:119], v[130:133], v[184:187], v[116:119]
	v_mfma_f32_16x16x32_bf16 v[112:115], v[162:165], v[184:187], v[112:115]
	v_mfma_f32_16x16x32_bf16 v[108:111], v[130:133], v[192:195], v[108:111]
	v_mfma_f32_16x16x32_bf16 v[104:107], v[162:165], v[192:195], v[104:107]
	v_mfma_f32_16x16x32_bf16 v[96:99], v[162:165], v[200:203], v[96:99]
	v_mfma_f32_16x16x32_bf16 v[124:127], v[156:159], v[180:183], v[124:127]
	v_mfma_f32_16x16x32_bf16 v[120:123], v[172:175], v[180:183], v[120:123]
	v_mfma_f32_16x16x32_bf16 v[116:119], v[156:159], v[188:191], v[116:119]
	v_mfma_f32_16x16x32_bf16 v[112:115], v[172:175], v[188:191], v[112:115]
	v_mfma_f32_16x16x32_bf16 v[108:111], v[156:159], v[196:199], v[108:111]
	v_mfma_f32_16x16x32_bf16 v[104:107], v[172:175], v[196:199], v[104:107]
	v_mfma_f32_16x16x32_bf16 v[100:103], v[130:133], v[200:203], v[100:103]
	v_mfma_f32_16x16x32_bf16 v[96:99], v[172:175], v[204:207], v[96:99]
	v_mfma_f32_16x16x32_bf16 v[100:103], v[156:159], v[204:207], v[100:103]
	s_barrier
; #define WAIT_V(n) asm volatile("s_waitcnt vmcnt(" #n ")" ::: "memory")
; #define WAIT_L(n) asm volatile("s_waitcnt lgkmcnt(" #n ")" ::: "memory")
; #define BAR __builtin_amdgcn_s_barrier()
;     ...
;     LDB(B1, 0, 1); BAR; WAIT_L(0); MMA(0, 1, At, B1); BAR;
;     LDA(At, 0, 1); WAIT_V(4); BAR; WAIT_L(0); MMA(1, 0, At, B0); MMA(1, 1, At, B1); BAR; }
;   { LDB(B0, 1, 0); LDA(At, 1, 0); WAIT_V(2); BAR; WAIT_L(0); MMA(0, 0, At, B0); BAR;
	ds_read_b128 v[208:211], v168
	ds_read_b128 v[212:215], v168 offset:1024
	ds_read_b128 v[216:219], v168 offset:2048
	ds_read_b128 v[166:169], v168 offset:3072
	s_barrier
	s_waitcnt lgkmcnt(0)
	s_waitcnt lgkmcnt(0)
	v_mfma_f32_16x16x32_bf16 v[92:95], v[208:211], v[176:179], v[92:95]
	v_mfma_f32_16x16x32_bf16 v[88:91], v[216:219], v[176:179], v[88:91]
	v_mfma_f32_16x16x32_bf16 v[84:87], v[208:211], v[184:187], v[84:87]
	v_mfma_f32_16x16x32_bf16 v[80:83], v[216:219], v[184:187], v[80:83]
	v_mfma_f32_16x16x32_bf16 v[76:79], v[208:211], v[192:195], v[76:79]
	v_mfma_f32_16x16x32_bf16 v[72:75], v[216:219], v[192:195], v[72:75]
	v_mfma_f32_16x16x32_bf16 v[68:71], v[208:211], v[200:203], v[68:71]
	v_mfma_f32_16x16x32_bf16 v[92:95], v[212:215], v[180:183], v[92:95]
	v_mfma_f32_16x16x32_bf16 v[88:91], v[166:169], v[180:183], v[88:91]
	v_mfma_f32_16x16x32_bf16 v[84:87], v[212:215], v[188:191], v[84:87]
	v_mfma_f32_16x16x32_bf16 v[80:83], v[166:169], v[188:191], v[80:83]
	v_mfma_f32_16x16x32_bf16 v[76:79], v[212:215], v[196:199], v[76:79]
	v_mfma_f32_16x16x32_bf16 v[176:179], v[166:169], v[196:199], v[72:75]
	v_mfma_f32_16x16x32_bf16 v[68:71], v[212:215], v[204:207], v[68:71]
	v_mfma_f32_16x16x32_bf16 v[64:67], v[216:219], v[200:203], v[64:67]
	v_mfma_f32_16x16x32_bf16 v[180:183], v[166:169], v[204:207], v[64:67]
	s_barrier
	s_nop 4
	ds_read_b128 v[64:67], v147 offset:16384
	ds_read_b128 v[72:75], v147 offset:17408
	ds_read_b128 v[184:187], v146 offset:16384
	ds_read_b128 v[188:191], v146 offset:17408
	ds_read_b128 v[192:195], v145 offset:16384
	ds_read_b128 v[196:199], v145 offset:17408
	ds_read_b128 v[200:203], v144 offset:16384
	ds_read_b128 v[204:207], v144 offset:17408
	s_waitcnt vmcnt(4)
	s_barrier
	s_waitcnt lgkmcnt(0)
	s_waitcnt lgkmcnt(0)
	v_mfma_f32_16x16x32_bf16 v[60:63], v[130:133], v[64:67], v[60:63]
	v_mfma_f32_16x16x32_bf16 v[36:39], v[130:133], v[200:203], v[36:39]
	v_mfma_f32_16x16x32_bf16 v[32:35], v[162:165], v[200:203], v[32:35]
	v_mfma_f32_16x16x32_bf16 v[60:63], v[156:159], v[72:75], v[60:63]
	v_mfma_f32_16x16x32_bf16 v[56:59], v[162:165], v[64:67], v[56:59]
	v_mfma_f32_16x16x32_bf16 v[52:55], v[130:133], v[184:187], v[52:55]
	v_mfma_f32_16x16x32_bf16 v[48:51], v[162:165], v[184:187], v[48:51]
	v_mfma_f32_16x16x32_bf16 v[44:47], v[130:133], v[192:195], v[44:47]
	v_mfma_f32_16x16x32_bf16 v[40:43], v[162:165], v[192:195], v[40:43]
	v_mfma_f32_16x16x32_bf16 v[128:131], v[156:159], v[204:207], v[36:39]
	v_mfma_f32_16x16x32_bf16 v[132:135], v[172:175], v[204:207], v[32:35]
	v_mfma_f32_16x16x32_bf16 v[220:223], v[172:175], v[72:75], v[56:59]
	v_mfma_f32_16x16x32_bf16 v[224:227], v[156:159], v[188:191], v[52:55]
	v_mfma_f32_16x16x32_bf16 v[228:231], v[172:175], v[188:191], v[48:51]
	v_mfma_f32_16x16x32_bf16 v[232:235], v[156:159], v[196:199], v[44:47]
	v_mfma_f32_16x16x32_bf16 v[236:239], v[172:175], v[196:199], v[40:43]
	v_mfma_f32_16x16x32_bf16 v[28:31], v[208:211], v[64:67], v[28:31]
	v_mfma_f32_16x16x32_bf16 v[24:27], v[216:219], v[64:67], v[24:27]
	v_mfma_f32_16x16x32_bf16 v[20:23], v[208:211], v[184:187], v[20:23]
	v_mfma_f32_16x16x32_bf16 v[16:19], v[216:219], v[184:187], v[16:19]
	v_mfma_f32_16x16x32_bf16 v[12:15], v[208:211], v[192:195], v[12:15]
	v_mfma_f32_16x16x32_bf16 v[8:11], v[216:219], v[192:195], v[8:11]
	v_mfma_f32_16x16x32_bf16 v[4:7], v[208:211], v[200:203], v[4:7]
	v_mfma_f32_16x16x32_bf16 v[0:3], v[216:219], v[200:203], v[0:3]
	v_mfma_f32_16x16x32_bf16 v[156:159], v[212:215], v[72:75], v[28:31]
	v_mfma_f32_16x16x32_bf16 v[24:27], v[166:169], v[72:75], v[24:27]
	v_mfma_f32_16x16x32_bf16 v[162:165], v[212:215], v[188:191], v[20:23]
	v_mfma_f32_16x16x32_bf16 v[170:173], v[166:169], v[188:191], v[16:19]
	v_mfma_f32_16x16x32_bf16 v[12:15], v[212:215], v[196:199], v[12:15]
	v_mfma_f32_16x16x32_bf16 v[184:187], v[166:169], v[196:199], v[8:11]
	v_mfma_f32_16x16x32_bf16 v[188:191], v[212:215], v[204:207], v[4:7]
	v_mfma_f32_16x16x32_bf16 v[166:169], v[166:169], v[204:207], v[0:3]
	s_barrier
	ds_read_b128 v[192:195], v160
	ds_read_b128 v[196:199], v160 offset:1024
	ds_read_b128 v[200:203], v160 offset:2048
	ds_read_b128 v[204:207], v160 offset:3072
	ds_read_b128 v[32:35], v147 offset:32768
	ds_read_b128 v[48:51], v147 offset:33792
	ds_read_b128 v[52:55], v146 offset:32768
	ds_read_b128 v[64:67], v146 offset:33792
	ds_read_b128 v[208:211], v145 offset:32768
	ds_read_b128 v[212:215], v145 offset:33792
	ds_read_b128 v[216:219], v144 offset:32768
	ds_read_b128 v[240:243], v144 offset:33792
	s_waitcnt vmcnt(2)
	s_barrier
; #define WAIT_V(n) asm volatile("s_waitcnt vmcnt(" #n ")" ::: "memory")
; #define WAIT_L(n) asm volatile("s_waitcnt lgkmcnt(" #n ")" ::: "memory")
; #define BAR __builtin_amdgcn_s_barrier()
;     ...
;   { LDB(B0, 1, 0); LDA(At, 1, 0); WAIT_V(2); BAR; WAIT_L(0); MMA(0, 0, At, B0); BAR;
;     LDB(B1, 1, 1); WAIT_V(0); BAR; WAIT_L(0); MMA(0, 1, At, B1); BAR;
;     LDA(At, 1, 1); BAR; WAIT_L(0); MMA(1, 0, At, B0); MMA(1, 1, At, B1); BAR; }
;   if (wr == 0) BAR;
	s_waitcnt lgkmcnt(0)
	s_waitcnt lgkmcnt(0)
	v_mfma_f32_16x16x32_bf16 v[0:3], v[192:195], v[32:35], v[124:127]
	v_mfma_f32_16x16x32_bf16 v[4:7], v[200:203], v[32:35], v[120:123]
	v_mfma_f32_16x16x32_bf16 v[8:11], v[192:195], v[52:55], v[116:119]
	v_mfma_f32_16x16x32_bf16 v[16:19], v[200:203], v[52:55], v[112:115]
	v_mfma_f32_16x16x32_bf16 v[20:23], v[192:195], v[208:211], v[108:111]
	v_mfma_f32_16x16x32_bf16 v[28:31], v[200:203], v[208:211], v[104:107]
	v_mfma_f32_16x16x32_bf16 v[36:39], v[192:195], v[216:219], v[100:103]
	v_mfma_f32_16x16x32_bf16 v[40:43], v[200:203], v[216:219], v[96:99]
	v_mfma_f32_16x16x32_bf16 v[0:3], v[196:199], v[48:51], v[0:3]
	v_mfma_f32_16x16x32_bf16 v[4:7], v[204:207], v[48:51], v[4:7]
	v_mfma_f32_16x16x32_bf16 v[8:11], v[196:199], v[64:67], v[8:11]
	v_mfma_f32_16x16x32_bf16 v[16:19], v[204:207], v[64:67], v[16:19]
	v_mfma_f32_16x16x32_bf16 v[20:23], v[196:199], v[212:215], v[20:23]
	v_mfma_f32_16x16x32_bf16 v[28:31], v[204:207], v[212:215], v[28:31]
	v_mfma_f32_16x16x32_bf16 v[36:39], v[196:199], v[240:243], v[36:39]
	v_mfma_f32_16x16x32_bf16 v[44:47], v[204:207], v[240:243], v[40:43]
	s_barrier
	ds_read_b128 v[244:247], v155
	ds_read_b128 v[248:251], v155 offset:1024
	ds_read_b128 v[100:103], v155 offset:2048
	ds_read_b128 v[152:155], v155 offset:3072
	s_waitcnt vmcnt(0)
	s_barrier
	s_waitcnt lgkmcnt(0)
	s_waitcnt lgkmcnt(0)
	v_mfma_f32_16x16x32_bf16 v[40:43], v[244:247], v[32:35], v[92:95]
	v_mfma_f32_16x16x32_bf16 v[32:35], v[100:103], v[32:35], v[88:91]
	v_mfma_f32_16x16x32_bf16 v[40:43], v[248:251], v[48:51], v[40:43]
	v_mfma_f32_16x16x32_bf16 v[32:35], v[152:155], v[48:51], v[32:35]
	v_mfma_f32_16x16x32_bf16 v[48:51], v[244:247], v[52:55], v[84:87]
	v_mfma_f32_16x16x32_bf16 v[56:59], v[248:251], v[64:67], v[48:51]
	v_mfma_f32_16x16x32_bf16 v[48:51], v[100:103], v[52:55], v[80:83]
	v_mfma_f32_16x16x32_bf16 v[52:55], v[244:247], v[208:211], v[76:79]
	v_mfma_f32_16x16x32_bf16 v[72:75], v[248:251], v[212:215], v[52:55]
	v_mfma_f32_16x16x32_bf16 v[52:55], v[100:103], v[208:211], v[176:179]
	v_mfma_f32_16x16x32_bf16 v[48:51], v[152:155], v[64:67], v[48:51]
	v_mfma_f32_16x16x32_bf16 v[64:67], v[152:155], v[212:215], v[52:55]
	v_mfma_f32_16x16x32_bf16 v[52:55], v[244:247], v[216:219], v[68:71]
	v_mfma_f32_16x16x32_bf16 v[88:91], v[248:251], v[240:243], v[52:55]
	v_mfma_f32_16x16x32_bf16 v[52:55], v[100:103], v[216:219], v[180:183]
	v_mfma_f32_16x16x32_bf16 v[76:79], v[152:155], v[240:243], v[52:55]
	s_barrier
	ds_read_b128 v[96:99], v147 offset:49152
	ds_read_b128 v[108:111], v147 offset:50176
	ds_read_b128 v[120:123], v146 offset:49152
	ds_read_b128 v[124:127], v146 offset:50176
	ds_read_b128 v[178:181], v145 offset:49152
	ds_read_b128 v[208:211], v145 offset:50176
	ds_read_b128 v[212:215], v144 offset:49152
	ds_read_b128 v[144:147], v144 offset:50176
	s_barrier
	s_waitcnt lgkmcnt(0)
	s_waitcnt lgkmcnt(0)
	v_mfma_f32_16x16x32_bf16 v[104:107], v[192:195], v[212:215], v[128:131]
	v_mfma_f32_16x16x32_bf16 v[52:55], v[192:195], v[96:99], v[60:63]
	v_mfma_f32_16x16x32_bf16 v[60:63], v[200:203], v[96:99], v[220:223]
	v_mfma_f32_16x16x32_bf16 v[68:71], v[192:195], v[120:123], v[224:227]
	v_mfma_f32_16x16x32_bf16 v[80:83], v[200:203], v[120:123], v[228:231]
	v_mfma_f32_16x16x32_bf16 v[84:87], v[192:195], v[178:181], v[232:235]
	v_mfma_f32_16x16x32_bf16 v[92:95], v[200:203], v[178:181], v[236:239]
	v_mfma_f32_16x16x32_bf16 v[174:177], v[196:199], v[144:147], v[104:107]
	v_mfma_f32_16x16x32_bf16 v[104:107], v[200:203], v[212:215], v[132:135]
	v_mfma_f32_16x16x32_bf16 v[52:55], v[196:199], v[108:111], v[52:55]
	v_mfma_f32_16x16x32_bf16 v[60:63], v[204:207], v[108:111], v[60:63]
	v_mfma_f32_16x16x32_bf16 v[68:71], v[196:199], v[124:127], v[68:71]
	v_mfma_f32_16x16x32_bf16 v[80:83], v[204:207], v[124:127], v[80:83]
	v_mfma_f32_16x16x32_bf16 v[84:87], v[196:199], v[208:211], v[84:87]
	v_mfma_f32_16x16x32_bf16 v[92:95], v[204:207], v[208:211], v[92:95]
	v_mfma_f32_16x16x32_bf16 v[112:115], v[204:207], v[144:147], v[104:107]
	v_mfma_f32_16x16x32_bf16 v[24:27], v[100:103], v[96:99], v[24:27]
	v_mfma_f32_16x16x32_bf16 v[104:107], v[244:247], v[96:99], v[156:159]
	v_mfma_f32_16x16x32_bf16 v[96:99], v[152:155], v[108:111], v[24:27]
	v_mfma_f32_16x16x32_bf16 v[24:27], v[244:247], v[120:123], v[162:165]
	v_mfma_f32_16x16x32_bf16 v[116:119], v[248:251], v[124:127], v[24:27]
	v_mfma_f32_16x16x32_bf16 v[24:27], v[100:103], v[120:123], v[170:173]
	v_mfma_f32_16x16x32_bf16 v[12:15], v[244:247], v[178:181], v[12:15]
	v_mfma_f32_16x16x32_bf16 v[104:107], v[248:251], v[108:111], v[104:107]
	v_mfma_f32_16x16x32_bf16 v[108:111], v[152:155], v[124:127], v[24:27]
	v_mfma_f32_16x16x32_bf16 v[124:127], v[248:251], v[208:211], v[12:15]
	v_mfma_f32_16x16x32_bf16 v[12:15], v[100:103], v[178:181], v[184:187]
	v_mfma_f32_16x16x32_bf16 v[120:123], v[152:155], v[208:211], v[12:15]
	v_mfma_f32_16x16x32_bf16 v[12:15], v[244:247], v[212:215], v[188:191]
	v_mfma_f32_16x16x32_bf16 v[132:135], v[248:251], v[144:147], v[12:15]
	v_mfma_f32_16x16x32_bf16 v[12:15], v[100:103], v[212:215], v[166:169]
	v_mfma_f32_16x16x32_bf16 v[128:131], v[152:155], v[144:147], v[12:15]
	v_cmp_gt_u32_e32 vcc, s41, v150
	s_barrier
	s_and_saveexec_b64 s[28:29], vcc
	s_cbranch_execz .LBB0_1145
	s_barrier

; #define WAIT_V(n) asm volatile("s_waitcnt vmcnt(" #n ")" ::: "memory")
; #define WAIT_L(n) asm volatile("s_waitcnt lgkmcnt(" #n ")" ::: "memory")
; #define BAR __builtin_amdgcn_s_barrier()
; #define SCHED __builtin_amdgcn_sched_barrier(0)
;     ...
;     LDB(B0, 0, 0); SCHED; LDA(At, 0, 0); STAGE(SA(1, 1), A, brow + HALF, t + 1);
;     WAIT_L(8); BAR; WAIT_L(0); MMA(0, 0, At, B0); BAR; SCHED;
;     LDB(B1, 0, 1); STAGE(SB(0, 0), Bt, bcol, t + 2);
;     BAR; WAIT_L(0); MMA(0, 1, At, B1); BAR;
;     LDA(At, 0, 1); STAGE(SA(0, 0), A, brow, t + 2);
;     BAR; WAIT_L(0); MMA(1, 0, At, B0); BAR; SCHED;
;     STAGE(SB(0, 1), Bt, bcol1, t + 2);
;     WAIT_V(6); BAR; MMA(1, 1, At, B1); BAR;
.LBB0_1236:
	ds_read_b128 v[176:179], v173
	ds_read_b128 v[180:183], v173 offset:1024
	ds_read_b128 v[184:187], v173 offset:2048
	ds_read_b128 v[188:191], v173 offset:3072
	v_add_u32_e32 v174, 0xc000, v154
	v_add_u32_e32 v175, 0xe000, v154
	s_add_u32 m0, s12, 0xc000
	ds_read_b128 v[192:195], v153
	ds_read_b128 v[196:199], v153 offset:1024
	ds_read_b128 v[200:203], v152
	ds_read_b128 v[204:207], v152 offset:1024
	ds_read_b128 v[208:211], v151
	ds_read_b128 v[212:215], v151 offset:1024
	ds_read_b128 v[216:219], v150
	ds_read_b128 v[220:223], v150 offset:1024
	global_load_lds_dwordx4 v159, s[64:65]
	s_add_u32 s64, s64, 0x100
	s_addc_u32 s65, s65, 0
	s_add_u32 m0, s12, 0xe000
	s_nop 0
	global_load_lds_dwordx4 v160, s[66:67]
	s_add_u32 s66, s66, 0x100
	s_addc_u32 s67, s67, 0
	s_waitcnt lgkmcnt(8)
	s_barrier
	s_waitcnt lgkmcnt(0)
	v_mfma_f32_16x16x32_bf16 v[124:127], v[176:179], v[192:195], v[124:127]
	v_mfma_f32_16x16x32_bf16 v[120:123], v[184:187], v[192:195], v[120:123]
	v_mfma_f32_16x16x32_bf16 v[116:119], v[176:179], v[200:203], v[116:119]
	v_mfma_f32_16x16x32_bf16 v[112:115], v[184:187], v[200:203], v[112:115]
	v_mfma_f32_16x16x32_bf16 v[108:111], v[176:179], v[208:211], v[108:111]
	v_mfma_f32_16x16x32_bf16 v[104:107], v[184:187], v[208:211], v[104:107]
	v_mfma_f32_16x16x32_bf16 v[100:103], v[176:179], v[216:219], v[100:103]
	v_mfma_f32_16x16x32_bf16 v[96:99], v[184:187], v[216:219], v[96:99]
	v_mfma_f32_16x16x32_bf16 v[124:127], v[180:183], v[196:199], v[124:127]
	v_mfma_f32_16x16x32_bf16 v[120:123], v[188:191], v[196:199], v[120:123]
	v_mfma_f32_16x16x32_bf16 v[116:119], v[180:183], v[204:207], v[116:119]
	v_mfma_f32_16x16x32_bf16 v[112:115], v[188:191], v[204:207], v[112:115]
	v_mfma_f32_16x16x32_bf16 v[108:111], v[180:183], v[212:215], v[108:111]
	v_mfma_f32_16x16x32_bf16 v[104:107], v[188:191], v[212:215], v[104:107]
	v_mfma_f32_16x16x32_bf16 v[100:103], v[180:183], v[220:223], v[100:103]
	v_mfma_f32_16x16x32_bf16 v[96:99], v[188:191], v[220:223], v[96:99]
	s_barrier
	s_add_u32 m0, s12, s33
	ds_read_b128 v[224:227], v172
	ds_read_b128 v[228:231], v172 offset:1024
	ds_read_b128 v[232:235], v172 offset:2048
	ds_read_b128 v[236:239], v172 offset:3072
	global_load_lds_dwordx4 v157, s[68:69]
	s_add_u32 s68, s68, 0x100
	s_addc_u32 s69, s69, 0
	s_add_u32 m0, s12, 0x2000
	s_add_u32 m0, m0, s33
	s_nop 0
	global_load_lds_dwordx4 v158, s[70:71]
	s_add_u32 s70, s70, 0x100
	s_addc_u32 s71, s71, 0
	s_barrier
	s_waitcnt lgkmcnt(0)
	v_mfma_f32_16x16x32_bf16 v[92:95], v[224:227], v[192:195], v[92:95]
	v_mfma_f32_16x16x32_bf16 v[88:91], v[232:235], v[192:195], v[88:91]
	v_mfma_f32_16x16x32_bf16 v[84:87], v[224:227], v[200:203], v[84:87]
	v_mfma_f32_16x16x32_bf16 v[80:83], v[232:235], v[200:203], v[80:83]
	v_mfma_f32_16x16x32_bf16 v[76:79], v[224:227], v[208:211], v[76:79]
	v_mfma_f32_16x16x32_bf16 v[72:75], v[232:235], v[208:211], v[72:75]
	v_mfma_f32_16x16x32_bf16 v[68:71], v[224:227], v[216:219], v[68:71]
	v_mfma_f32_16x16x32_bf16 v[64:67], v[232:235], v[216:219], v[64:67]
	v_mfma_f32_16x16x32_bf16 v[92:95], v[228:231], v[196:199], v[92:95]
	v_mfma_f32_16x16x32_bf16 v[88:91], v[236:239], v[196:199], v[88:91]
	v_mfma_f32_16x16x32_bf16 v[84:87], v[228:231], v[204:207], v[84:87]
	v_mfma_f32_16x16x32_bf16 v[80:83], v[236:239], v[204:207], v[80:83]
	v_mfma_f32_16x16x32_bf16 v[76:79], v[228:231], v[212:215], v[76:79]
	v_mfma_f32_16x16x32_bf16 v[72:75], v[236:239], v[212:215], v[72:75]
	v_mfma_f32_16x16x32_bf16 v[68:71], v[228:231], v[220:223], v[68:71]
	v_mfma_f32_16x16x32_bf16 v[64:67], v[236:239], v[220:223], v[64:67]
	s_mov_b32 m0, s12
	s_barrier
	ds_read_b128 v[192:195], v153 offset:16384
	ds_read_b128 v[196:199], v153 offset:17408
	ds_read_b128 v[200:203], v152 offset:16384
	ds_read_b128 v[204:207], v152 offset:17408
	ds_read_b128 v[208:211], v151 offset:16384
	ds_read_b128 v[212:215], v151 offset:17408
	ds_read_b128 v[216:219], v150 offset:16384
	ds_read_b128 v[220:223], v150 offset:17408
	global_load_lds_dwordx4 v159, s[72:73]
	s_add_u32 s72, s72, 0x100
	s_addc_u32 s73, s73, 0
	s_add_u32 m0, s12, 0x2000
	s_nop 0
	global_load_lds_dwordx4 v160, s[74:75]
	s_add_u32 s74, s74, 0x100
	s_addc_u32 s75, s75, 0
	s_barrier
	s_waitcnt lgkmcnt(0)
	v_mfma_f32_16x16x32_bf16 v[60:63], v[176:179], v[192:195], v[60:63]
	v_mfma_f32_16x16x32_bf16 v[56:59], v[184:187], v[192:195], v[56:59]
	v_mfma_f32_16x16x32_bf16 v[52:55], v[176:179], v[200:203], v[52:55]
	v_mfma_f32_16x16x32_bf16 v[48:51], v[184:187], v[200:203], v[48:51]
	v_mfma_f32_16x16x32_bf16 v[44:47], v[176:179], v[208:211], v[44:47]
	v_mfma_f32_16x16x32_bf16 v[40:43], v[184:187], v[208:211], v[40:43]
	v_mfma_f32_16x16x32_bf16 v[36:39], v[176:179], v[216:219], v[36:39]
	v_mfma_f32_16x16x32_bf16 v[32:35], v[184:187], v[216:219], v[32:35]
	v_mfma_f32_16x16x32_bf16 v[60:63], v[180:183], v[196:199], v[60:63]
	v_mfma_f32_16x16x32_bf16 v[56:59], v[188:191], v[196:199], v[56:59]
	v_mfma_f32_16x16x32_bf16 v[52:55], v[180:183], v[204:207], v[52:55]
	v_mfma_f32_16x16x32_bf16 v[48:51], v[188:191], v[204:207], v[48:51]
	v_mfma_f32_16x16x32_bf16 v[44:47], v[180:183], v[212:215], v[44:47]
	v_mfma_f32_16x16x32_bf16 v[40:43], v[188:191], v[212:215], v[40:43]
	v_mfma_f32_16x16x32_bf16 v[36:39], v[180:183], v[220:223], v[36:39]
	v_mfma_f32_16x16x32_bf16 v[32:35], v[188:191], v[220:223], v[32:35]
	s_barrier
	s_add_u32 m0, s12, s58
	s_nop 0
	global_load_lds_dwordx4 v162, s[76:77]
	s_add_u32 s76, s76, 0x100
	s_addc_u32 s77, s77, 0
	s_add_u32 m0, s12, 0x2000
	s_add_u32 m0, m0, s58
	s_nop 0
	global_load_lds_dwordx4 v163, s[78:79]
	s_add_u32 s78, s78, 0x100
	s_addc_u32 s79, s79, 0
	s_waitcnt vmcnt(6)
	s_barrier
; #define WAIT_V(n) asm volatile("s_waitcnt vmcnt(" #n ")" ::: "memory")
; #define WAIT_L(n) asm volatile("s_waitcnt lgkmcnt(" #n ")" ::: "memory")
; #define BAR __builtin_amdgcn_s_barrier()
; #define SCHED __builtin_amdgcn_sched_barrier(0)
;     ...
;     WAIT_V(6); BAR; MMA(1, 1, At, B1); BAR;
;     LDB(B0, 1, 0); SCHED; LDA(At, 1, 0); STAGE(SA(0, 1), A, brow + HALF, t + 2);
;     WAIT_L(8); BAR; WAIT_L(0); MMA(0, 0, At, B0); BAR; SCHED;
;     LDB(B1, 1, 1); STAGE(SB(1, 0), Bt, bcol, t + 3);
;     BAR; WAIT_L(0); MMA(0, 1, At, B1); BAR;
;     LDA(At, 1, 1); STAGE(SA(1, 0), A, brow, t + 3);
	v_mfma_f32_16x16x32_bf16 v[28:31], v[224:227], v[192:195], v[28:31]
	v_mfma_f32_16x16x32_bf16 v[24:27], v[232:235], v[192:195], v[24:27]
	v_mfma_f32_16x16x32_bf16 v[20:23], v[224:227], v[200:203], v[20:23]
	v_mfma_f32_16x16x32_bf16 v[16:19], v[232:235], v[200:203], v[16:19]
	v_mfma_f32_16x16x32_bf16 v[12:15], v[224:227], v[208:211], v[12:15]
	v_mfma_f32_16x16x32_bf16 v[8:11], v[232:235], v[208:211], v[8:11]
	v_mfma_f32_16x16x32_bf16 v[4:7], v[224:227], v[216:219], v[4:7]
	v_mfma_f32_16x16x32_bf16 v[0:3], v[232:235], v[216:219], v[0:3]
	v_mfma_f32_16x16x32_bf16 v[28:31], v[228:231], v[196:199], v[28:31]
	v_mfma_f32_16x16x32_bf16 v[24:27], v[236:239], v[196:199], v[24:27]
	v_mfma_f32_16x16x32_bf16 v[20:23], v[228:231], v[204:207], v[20:23]
	v_mfma_f32_16x16x32_bf16 v[16:19], v[236:239], v[204:207], v[16:19]
	v_mfma_f32_16x16x32_bf16 v[12:15], v[228:231], v[212:215], v[12:15]
	v_mfma_f32_16x16x32_bf16 v[8:11], v[236:239], v[212:215], v[8:11]
	v_mfma_f32_16x16x32_bf16 v[4:7], v[228:231], v[220:223], v[4:7]
	v_mfma_f32_16x16x32_bf16 v[0:3], v[236:239], v[220:223], v[0:3]
	s_barrier
	ds_read_b128 v[176:179], v161
	ds_read_b128 v[180:183], v161 offset:1024
	ds_read_b128 v[184:187], v161 offset:2048
	ds_read_b128 v[188:191], v161 offset:3072
	s_add_u32 m0, s12, 0x4000
	ds_read_b128 v[192:195], v153 offset:32768
	ds_read_b128 v[196:199], v153 offset:33792
	ds_read_b128 v[200:203], v152 offset:32768
	ds_read_b128 v[204:207], v152 offset:33792
	ds_read_b128 v[208:211], v151 offset:32768
	ds_read_b128 v[212:215], v151 offset:33792
	ds_read_b128 v[216:219], v150 offset:32768
	ds_read_b128 v[220:223], v150 offset:33792
	global_load_lds_dwordx4 v159, s[80:81]
	s_add_u32 s80, s80, 0x100
	s_addc_u32 s81, s81, 0
	s_add_u32 m0, s12, 0x6000
	s_nop 0
	global_load_lds_dwordx4 v160, s[82:83]
	s_add_u32 s82, s82, 0x100
	s_addc_u32 s83, s83, 0
	s_waitcnt lgkmcnt(8)
	s_barrier
	s_waitcnt lgkmcnt(0)
	v_mfma_f32_16x16x32_bf16 v[124:127], v[176:179], v[192:195], v[124:127]
	v_mfma_f32_16x16x32_bf16 v[120:123], v[184:187], v[192:195], v[120:123]
	v_mfma_f32_16x16x32_bf16 v[116:119], v[176:179], v[200:203], v[116:119]
	v_mfma_f32_16x16x32_bf16 v[112:115], v[184:187], v[200:203], v[112:115]
	v_mfma_f32_16x16x32_bf16 v[108:111], v[176:179], v[208:211], v[108:111]
	v_mfma_f32_16x16x32_bf16 v[104:107], v[184:187], v[208:211], v[104:107]
	v_mfma_f32_16x16x32_bf16 v[100:103], v[176:179], v[216:219], v[100:103]
	v_mfma_f32_16x16x32_bf16 v[96:99], v[184:187], v[216:219], v[96:99]
	v_mfma_f32_16x16x32_bf16 v[124:127], v[180:183], v[196:199], v[124:127]
	v_mfma_f32_16x16x32_bf16 v[120:123], v[188:191], v[196:199], v[120:123]
	v_mfma_f32_16x16x32_bf16 v[116:119], v[180:183], v[204:207], v[116:119]
	v_mfma_f32_16x16x32_bf16 v[112:115], v[188:191], v[204:207], v[112:115]
	v_mfma_f32_16x16x32_bf16 v[108:111], v[180:183], v[212:215], v[108:111]
	v_mfma_f32_16x16x32_bf16 v[104:107], v[188:191], v[212:215], v[104:107]
	v_mfma_f32_16x16x32_bf16 v[100:103], v[180:183], v[220:223], v[100:103]
	v_mfma_f32_16x16x32_bf16 v[96:99], v[188:191], v[220:223], v[96:99]
	s_barrier
	s_add_u32 m0, s12, s59
	ds_read_b128 v[224:227], v156
	ds_read_b128 v[228:231], v156 offset:1024
	ds_read_b128 v[232:235], v156 offset:2048
	ds_read_b128 v[236:239], v156 offset:3072
	global_load_lds_dwordx4 v157, s[84:85]
	s_add_u32 s84, s84, 0x100
	s_addc_u32 s85, s85, 0
	s_add_u32 m0, s12, 0x2000
	s_add_u32 m0, m0, s59
	s_nop 0
	global_load_lds_dwordx4 v158, s[86:87]
	s_add_u32 s86, s86, 0x100
	s_addc_u32 s87, s87, 0
	s_barrier
	s_waitcnt lgkmcnt(0)
	v_mfma_f32_16x16x32_bf16 v[92:95], v[224:227], v[192:195], v[92:95]
	v_mfma_f32_16x16x32_bf16 v[88:91], v[232:235], v[192:195], v[88:91]
	v_mfma_f32_16x16x32_bf16 v[84:87], v[224:227], v[200:203], v[84:87]
	v_mfma_f32_16x16x32_bf16 v[80:83], v[232:235], v[200:203], v[80:83]
	v_mfma_f32_16x16x32_bf16 v[76:79], v[224:227], v[208:211], v[76:79]
	v_mfma_f32_16x16x32_bf16 v[72:75], v[232:235], v[208:211], v[72:75]
	v_mfma_f32_16x16x32_bf16 v[68:71], v[224:227], v[216:219], v[68:71]
	v_mfma_f32_16x16x32_bf16 v[64:67], v[232:235], v[216:219], v[64:67]
	v_mfma_f32_16x16x32_bf16 v[92:95], v[228:231], v[196:199], v[92:95]
	v_mfma_f32_16x16x32_bf16 v[88:91], v[236:239], v[196:199], v[88:91]
	v_mfma_f32_16x16x32_bf16 v[84:87], v[228:231], v[204:207], v[84:87]
	v_mfma_f32_16x16x32_bf16 v[80:83], v[236:239], v[204:207], v[80:83]
	v_mfma_f32_16x16x32_bf16 v[76:79], v[228:231], v[212:215], v[76:79]
	v_mfma_f32_16x16x32_bf16 v[72:75], v[236:239], v[212:215], v[72:75]
	v_mfma_f32_16x16x32_bf16 v[68:71], v[228:231], v[220:223], v[68:71]
	v_mfma_f32_16x16x32_bf16 v[64:67], v[236:239], v[220:223], v[64:67]
	s_add_u32 m0, s12, 0x8000
	s_barrier
	ds_read_b128 v[192:195], v153 offset:49152
	ds_read_b128 v[196:199], v153 offset:50176
	ds_read_b128 v[200:203], v152 offset:49152
	ds_read_b128 v[204:207], v152 offset:50176
	ds_read_b128 v[208:211], v151 offset:49152
	ds_read_b128 v[212:215], v151 offset:50176
	ds_read_b128 v[216:219], v150 offset:49152
	ds_read_b128 v[220:223], v150 offset:50176
	global_load_lds_dwordx4 v159, s[88:89]
	s_add_u32 s88, s88, 0x100
	s_addc_u32 s89, s89, 0
	s_add_u32 m0, s12, 0xa000
	s_nop 0
	global_load_lds_dwordx4 v160, s[90:91]
	s_add_u32 s90, s90, 0x100
	s_addc_u32 s91, s91, 0
	s_barrier
; #define WAIT_V(n) asm volatile("s_waitcnt vmcnt(" #n ")" ::: "memory")
; #define WAIT_L(n) asm volatile("s_waitcnt lgkmcnt(" #n ")" ::: "memory")
; #define BAR __builtin_amdgcn_s_barrier()
; #define SCHED __builtin_amdgcn_sched_barrier(0)
;     ...
;     BAR; WAIT_L(0); MMA(1, 0, At, B0); BAR; SCHED;
;     STAGE(SB(1, 1), Bt, bcol1, t + 3);
;     WAIT_V(6); BAR; MMA(1, 1, At, B1); BAR;
;   }
;   { LDB(B0, 0, 0); LDA(At, 0, 0); STAGE(SA(1, 1), A, brow + HALF, nt - 1);
;     BAR; WAIT_L(0); MMA(0, 0, At, B0); BAR;
	s_waitcnt lgkmcnt(0)
	v_mfma_f32_16x16x32_bf16 v[60:63], v[176:179], v[192:195], v[60:63]
	v_mfma_f32_16x16x32_bf16 v[56:59], v[184:187], v[192:195], v[56:59]
	v_mfma_f32_16x16x32_bf16 v[52:55], v[176:179], v[200:203], v[52:55]
	v_mfma_f32_16x16x32_bf16 v[48:51], v[184:187], v[200:203], v[48:51]
	v_mfma_f32_16x16x32_bf16 v[44:47], v[176:179], v[208:211], v[44:47]
	v_mfma_f32_16x16x32_bf16 v[40:43], v[184:187], v[208:211], v[40:43]
	v_mfma_f32_16x16x32_bf16 v[36:39], v[176:179], v[216:219], v[36:39]
	v_mfma_f32_16x16x32_bf16 v[32:35], v[184:187], v[216:219], v[32:35]
	v_mfma_f32_16x16x32_bf16 v[60:63], v[180:183], v[196:199], v[60:63]
	v_mfma_f32_16x16x32_bf16 v[56:59], v[188:191], v[196:199], v[56:59]
	v_mfma_f32_16x16x32_bf16 v[52:55], v[180:183], v[204:207], v[52:55]
	v_mfma_f32_16x16x32_bf16 v[48:51], v[188:191], v[204:207], v[48:51]
	v_mfma_f32_16x16x32_bf16 v[44:47], v[180:183], v[212:215], v[44:47]
	v_mfma_f32_16x16x32_bf16 v[40:43], v[188:191], v[212:215], v[40:43]
	v_mfma_f32_16x16x32_bf16 v[36:39], v[180:183], v[220:223], v[36:39]
	v_mfma_f32_16x16x32_bf16 v[32:35], v[188:191], v[220:223], v[32:35]
	s_barrier
	s_add_u32 m0, s12, s60
	s_nop 0
	global_load_lds_dwordx4 v162, s[92:93]
	s_add_u32 s92, s92, 0x100
	s_addc_u32 s93, s93, 0
	s_add_u32 m0, s12, 0x2000
	s_add_u32 m0, m0, s60
	s_nop 0
	global_load_lds_dwordx4 v163, s[94:95]
	s_add_u32 s94, s94, 0x100
	s_addc_u32 s95, s95, 0
	s_waitcnt vmcnt(6)
	s_barrier
	v_mfma_f32_16x16x32_bf16 v[28:31], v[224:227], v[192:195], v[28:31]
	v_mfma_f32_16x16x32_bf16 v[24:27], v[232:235], v[192:195], v[24:27]
	v_mfma_f32_16x16x32_bf16 v[20:23], v[224:227], v[200:203], v[20:23]
	v_mfma_f32_16x16x32_bf16 v[16:19], v[232:235], v[200:203], v[16:19]
	v_mfma_f32_16x16x32_bf16 v[12:15], v[224:227], v[208:211], v[12:15]
	v_mfma_f32_16x16x32_bf16 v[8:11], v[232:235], v[208:211], v[8:11]
	v_mfma_f32_16x16x32_bf16 v[4:7], v[224:227], v[216:219], v[4:7]
	v_mfma_f32_16x16x32_bf16 v[0:3], v[232:235], v[216:219], v[0:3]
	v_mfma_f32_16x16x32_bf16 v[28:31], v[228:231], v[196:199], v[28:31]
	v_mfma_f32_16x16x32_bf16 v[24:27], v[236:239], v[196:199], v[24:27]
	v_mfma_f32_16x16x32_bf16 v[20:23], v[228:231], v[204:207], v[20:23]
	v_mfma_f32_16x16x32_bf16 v[16:19], v[236:239], v[204:207], v[16:19]
	v_mfma_f32_16x16x32_bf16 v[12:15], v[228:231], v[212:215], v[12:15]
	v_mfma_f32_16x16x32_bf16 v[8:11], v[236:239], v[212:215], v[8:11]
	v_mfma_f32_16x16x32_bf16 v[4:7], v[228:231], v[220:223], v[4:7]
	v_mfma_f32_16x16x32_bf16 v[0:3], v[236:239], v[220:223], v[0:3]
	s_add_i32 s7, s7, 2
	s_add_u32 s4, s4, 0x100
	s_addc_u32 s5, s5, 0
	s_cmp_lt_u32 s7, 60
	s_barrier
	s_cbranch_scc1 .LBB0_1236
	v_readlane_b32 s64, v254, 0
	v_readlane_b32 s65, v254, 1
	v_readlane_b32 s66, v254, 2
	v_readlane_b32 s67, v254, 3
	v_readlane_b32 s68, v254, 4
	v_readlane_b32 s69, v254, 5
	v_readlane_b32 s70, v254, 6
	v_readlane_b32 s71, v254, 7
	v_readlane_b32 s72, v254, 8
	v_readlane_b32 s73, v254, 9
	v_readlane_b32 s74, v254, 10
	v_readlane_b32 s75, v254, 11
	v_readlane_b32 s76, v254, 12
	v_readlane_b32 s77, v254, 13
	v_readlane_b32 s78, v254, 14
	v_readlane_b32 s79, v254, 15
	v_readlane_b32 s80, v254, 16
	v_readlane_b32 s81, v254, 17
	v_readlane_b32 s82, v254, 18
	v_readlane_b32 s83, v254, 19
	v_readlane_b32 s84, v254, 20
	v_readlane_b32 s85, v254, 21
	v_readlane_b32 s86, v254, 22
	v_readlane_b32 s87, v254, 23
	v_readlane_b32 s88, v254, 24
	v_readlane_b32 s89, v254, 25
	v_readlane_b32 s90, v254, 26
	v_readlane_b32 s91, v254, 27
	v_readlane_b32 s92, v254, 28
	v_readlane_b32 s93, v254, 29
	v_readlane_b32 s94, v254, 30
	v_readlane_b32 s95, v254, 31
	s_nop 4
	s_add_u32 s4, s8, 0x1f80
	s_addc_u32 s5, s9, 0
	v_readfirstlane_b32 s7, v174
	v_lshl_add_u64 v[142:143], s[4:5], 0, v[148:149]
	s_mov_b32 m0, s7
	v_lshl_add_u64 v[128:129], s[4:5], 0, v[128:129]
	v_readfirstlane_b32 s4, v175
	ds_read_b128 v[130:133], v173
	ds_read_b128 v[134:137], v173 offset:1024
	ds_read_b128 v[138:141], v173 offset:2048
	ds_read_b128 v[162:165], v173 offset:3072
	ds_read_b128 v[176:179], v153
	ds_read_b128 v[180:183], v153 offset:1024
	ds_read_b128 v[184:187], v152
	ds_read_b128 v[188:191], v152 offset:1024
	ds_read_b128 v[192:195], v151
	ds_read_b128 v[196:199], v151 offset:1024
	ds_read_b128 v[200:203], v150
	ds_read_b128 v[204:207], v150 offset:1024
	global_load_lds_dwordx4 v[142:143], off
	s_mov_b32 m0, s4
	s_nop 0
	global_load_lds_dwordx4 v[128:129], off
	s_barrier
	s_waitcnt lgkmcnt(0)
	s_waitcnt lgkmcnt(0)
	v_mfma_f32_16x16x32_bf16 v[116:119], v[130:133], v[184:187], v[116:119]
	v_mfma_f32_16x16x32_bf16 v[108:111], v[130:133], v[192:195], v[108:111]
	v_mfma_f32_16x16x32_bf16 v[100:103], v[130:133], v[200:203], v[100:103]
	v_mfma_f32_16x16x32_bf16 v[96:99], v[138:141], v[200:203], v[96:99]
	v_mfma_f32_16x16x32_bf16 v[124:127], v[130:133], v[176:179], v[124:127]
	v_mfma_f32_16x16x32_bf16 v[120:123], v[138:141], v[176:179], v[120:123]
	v_mfma_f32_16x16x32_bf16 v[116:119], v[134:137], v[188:191], v[116:119]
	v_mfma_f32_16x16x32_bf16 v[112:115], v[138:141], v[184:187], v[112:115]
	v_mfma_f32_16x16x32_bf16 v[108:111], v[134:137], v[196:199], v[108:111]
	v_mfma_f32_16x16x32_bf16 v[104:107], v[138:141], v[192:195], v[104:107]
	v_mfma_f32_16x16x32_bf16 v[100:103], v[134:137], v[204:207], v[100:103]
	v_mfma_f32_16x16x32_bf16 v[96:99], v[162:165], v[204:207], v[96:99]
	v_mfma_f32_16x16x32_bf16 v[124:127], v[134:137], v[180:183], v[124:127]
	v_mfma_f32_16x16x32_bf16 v[208:211], v[162:165], v[180:183], v[120:123]
	v_mfma_f32_16x16x32_bf16 v[212:215], v[162:165], v[188:191], v[112:115]
	v_mfma_f32_16x16x32_bf16 v[216:219], v[162:165], v[196:199], v[104:107]
	s_barrier
; #define WAIT_V(n) asm volatile("s_waitcnt vmcnt(" #n ")" ::: "memory")
; #define WAIT_L(n) asm volatile("s_waitcnt lgkmcnt(" #n ")" ::: "memory")
; #define BAR __builtin_amdgcn_s_barrier()
;     ...
;     LDB(B1, 0, 1); BAR; WAIT_L(0); MMA(0, 1, At, B1); BAR;
;     LDA(At, 0, 1); WAIT_V(4); BAR; WAIT_L(0); MMA(1, 0, At, B0); MMA(1, 1, At, B1); BAR; }
;   { LDB(B0, 1, 0); LDA(At, 1, 0); WAIT_V(2); BAR; WAIT_L(0); MMA(0, 0, At, B0); BAR;
	s_nop 0
	ds_read_b128 v[104:107], v172
	ds_read_b128 v[112:115], v172 offset:1024
	ds_read_b128 v[120:123], v172 offset:2048
	ds_read_b128 v[172:175], v172 offset:3072
	s_barrier
	s_waitcnt lgkmcnt(0)
	s_waitcnt lgkmcnt(0)
	v_mfma_f32_16x16x32_bf16 v[92:95], v[104:107], v[176:179], v[92:95]
	v_mfma_f32_16x16x32_bf16 v[84:87], v[104:107], v[184:187], v[84:87]
	v_mfma_f32_16x16x32_bf16 v[76:79], v[104:107], v[192:195], v[76:79]
	v_mfma_f32_16x16x32_bf16 v[64:67], v[120:123], v[200:203], v[64:67]
	v_mfma_f32_16x16x32_bf16 v[92:95], v[112:115], v[180:183], v[92:95]
	v_mfma_f32_16x16x32_bf16 v[88:91], v[120:123], v[176:179], v[88:91]
	v_mfma_f32_16x16x32_bf16 v[84:87], v[112:115], v[188:191], v[84:87]
	v_mfma_f32_16x16x32_bf16 v[80:83], v[120:123], v[184:187], v[80:83]
	v_mfma_f32_16x16x32_bf16 v[76:79], v[112:115], v[196:199], v[76:79]
	v_mfma_f32_16x16x32_bf16 v[72:75], v[120:123], v[192:195], v[72:75]
	v_mfma_f32_16x16x32_bf16 v[68:71], v[104:107], v[200:203], v[68:71]
	v_mfma_f32_16x16x32_bf16 v[64:67], v[172:175], v[204:207], v[64:67]
	v_mfma_f32_16x16x32_bf16 v[176:179], v[172:175], v[180:183], v[88:91]
	v_mfma_f32_16x16x32_bf16 v[180:183], v[172:175], v[188:191], v[80:83]
	v_mfma_f32_16x16x32_bf16 v[184:187], v[172:175], v[196:199], v[72:75]
	v_mfma_f32_16x16x32_bf16 v[188:191], v[112:115], v[204:207], v[68:71]
	s_barrier
	s_nop 0
	ds_read_b128 v[68:71], v153 offset:16384
	ds_read_b128 v[72:75], v153 offset:17408
	ds_read_b128 v[80:83], v152 offset:16384
	ds_read_b128 v[88:91], v152 offset:17408
	ds_read_b128 v[192:195], v151 offset:16384
	ds_read_b128 v[196:199], v151 offset:17408
	ds_read_b128 v[200:203], v150 offset:16384
	ds_read_b128 v[204:207], v150 offset:17408
	s_waitcnt vmcnt(4)
	s_barrier
	s_waitcnt lgkmcnt(0)
	s_waitcnt lgkmcnt(0)
	v_mfma_f32_16x16x32_bf16 v[60:63], v[130:133], v[68:71], v[60:63]
	v_mfma_f32_16x16x32_bf16 v[52:55], v[130:133], v[80:83], v[52:55]
	v_mfma_f32_16x16x32_bf16 v[44:47], v[130:133], v[192:195], v[44:47]
	v_mfma_f32_16x16x32_bf16 v[36:39], v[130:133], v[200:203], v[36:39]
	v_mfma_f32_16x16x32_bf16 v[32:35], v[138:141], v[200:203], v[32:35]
	v_mfma_f32_16x16x32_bf16 v[60:63], v[134:137], v[72:75], v[60:63]
	v_mfma_f32_16x16x32_bf16 v[56:59], v[138:141], v[68:71], v[56:59]
	v_mfma_f32_16x16x32_bf16 v[52:55], v[134:137], v[88:91], v[52:55]
	v_mfma_f32_16x16x32_bf16 v[48:51], v[138:141], v[80:83], v[48:51]
	v_mfma_f32_16x16x32_bf16 v[44:47], v[134:137], v[196:199], v[44:47]
	v_mfma_f32_16x16x32_bf16 v[40:43], v[138:141], v[192:195], v[40:43]
	v_mfma_f32_16x16x32_bf16 v[36:39], v[134:137], v[204:207], v[36:39]
	v_mfma_f32_16x16x32_bf16 v[32:35], v[162:165], v[204:207], v[32:35]
	v_mfma_f32_16x16x32_bf16 v[220:223], v[162:165], v[72:75], v[56:59]
	v_mfma_f32_16x16x32_bf16 v[224:227], v[162:165], v[88:91], v[48:51]
	v_mfma_f32_16x16x32_bf16 v[228:231], v[162:165], v[196:199], v[40:43]
	v_mfma_f32_16x16x32_bf16 v[28:31], v[104:107], v[68:71], v[28:31]
	v_mfma_f32_16x16x32_bf16 v[20:23], v[104:107], v[80:83], v[20:23]
	v_mfma_f32_16x16x32_bf16 v[12:15], v[104:107], v[192:195], v[12:15]
	v_mfma_f32_16x16x32_bf16 v[0:3], v[120:123], v[200:203], v[0:3]
	v_mfma_f32_16x16x32_bf16 v[28:31], v[112:115], v[72:75], v[28:31]
	v_mfma_f32_16x16x32_bf16 v[24:27], v[120:123], v[68:71], v[24:27]
	v_mfma_f32_16x16x32_bf16 v[20:23], v[112:115], v[88:91], v[20:23]
	v_mfma_f32_16x16x32_bf16 v[16:19], v[120:123], v[80:83], v[16:19]
	v_mfma_f32_16x16x32_bf16 v[12:15], v[112:115], v[196:199], v[12:15]
	v_mfma_f32_16x16x32_bf16 v[8:11], v[120:123], v[192:195], v[8:11]
	v_mfma_f32_16x16x32_bf16 v[4:7], v[104:107], v[200:203], v[4:7]
	v_mfma_f32_16x16x32_bf16 v[0:3], v[172:175], v[204:207], v[0:3]
	v_mfma_f32_16x16x32_bf16 v[128:131], v[172:175], v[72:75], v[24:27]
	v_mfma_f32_16x16x32_bf16 v[132:135], v[172:175], v[88:91], v[16:19]
	v_mfma_f32_16x16x32_bf16 v[136:139], v[172:175], v[196:199], v[8:11]
	v_mfma_f32_16x16x32_bf16 v[162:165], v[112:115], v[204:207], v[4:7]
	s_barrier
	s_nop 0
	ds_read_b128 v[4:7], v161
	ds_read_b128 v[172:175], v161 offset:1024
	ds_read_b128 v[192:195], v161 offset:2048
	ds_read_b128 v[158:161], v161 offset:3072
	ds_read_b128 v[8:11], v153 offset:32768
	ds_read_b128 v[16:19], v153 offset:33792
	ds_read_b128 v[24:27], v152 offset:32768
	ds_read_b128 v[40:43], v152 offset:33792
	ds_read_b128 v[48:51], v151 offset:32768
	ds_read_b128 v[56:59], v151 offset:33792
	ds_read_b128 v[196:199], v150 offset:32768
	ds_read_b128 v[200:203], v150 offset:33792
	s_waitcnt vmcnt(2)
	s_barrier
; #define WAIT_V(n) asm volatile("s_waitcnt vmcnt(" #n ")" ::: "memory")
; #define WAIT_L(n) asm volatile("s_waitcnt lgkmcnt(" #n ")" ::: "memory")
; #define BAR __builtin_amdgcn_s_barrier()
;     ...
;   { LDB(B0, 1, 0); LDA(At, 1, 0); WAIT_V(2); BAR; WAIT_L(0); MMA(0, 0, At, B0); BAR;
;     LDB(B1, 1, 1); WAIT_V(0); BAR; WAIT_L(0); MMA(0, 1, At, B1); BAR;
;     LDA(At, 1, 1); BAR; WAIT_L(0); MMA(1, 0, At, B0); MMA(1, 1, At, B1); BAR; }
;   if (wr == 0) BAR;
	s_waitcnt lgkmcnt(0)
	s_waitcnt lgkmcnt(0)
	v_mfma_f32_16x16x32_bf16 v[68:71], v[4:7], v[8:11], v[124:127]
	v_mfma_f32_16x16x32_bf16 v[120:123], v[172:175], v[16:19], v[68:71]
	v_mfma_f32_16x16x32_bf16 v[68:71], v[192:195], v[8:11], v[208:211]
	v_mfma_f32_16x16x32_bf16 v[88:91], v[158:161], v[16:19], v[68:71]
	v_mfma_f32_16x16x32_bf16 v[68:71], v[4:7], v[24:27], v[116:119]
	v_mfma_f32_16x16x32_bf16 v[112:115], v[172:175], v[40:43], v[68:71]
	v_mfma_f32_16x16x32_bf16 v[68:71], v[192:195], v[24:27], v[212:215]
	v_mfma_f32_16x16x32_bf16 v[80:83], v[158:161], v[40:43], v[68:71]
	v_mfma_f32_16x16x32_bf16 v[68:71], v[4:7], v[48:51], v[108:111]
	v_mfma_f32_16x16x32_bf16 v[104:107], v[172:175], v[56:59], v[68:71]
	v_mfma_f32_16x16x32_bf16 v[68:71], v[192:195], v[48:51], v[216:219]
	v_mfma_f32_16x16x32_bf16 v[72:75], v[158:161], v[56:59], v[68:71]
	v_mfma_f32_16x16x32_bf16 v[68:71], v[4:7], v[196:199], v[100:103]
	v_mfma_f32_16x16x32_bf16 v[100:103], v[172:175], v[200:203], v[68:71]
	v_mfma_f32_16x16x32_bf16 v[68:71], v[192:195], v[196:199], v[96:99]
	v_mfma_f32_16x16x32_bf16 v[68:71], v[158:161], v[200:203], v[68:71]
	s_barrier
	ds_read_b128 v[124:127], v156
	ds_read_b128 v[204:207], v156 offset:1024
	ds_read_b128 v[208:211], v156 offset:2048
	ds_read_b128 v[154:157], v156 offset:3072
	s_waitcnt vmcnt(0)
	s_barrier
	s_waitcnt lgkmcnt(0)
	s_waitcnt lgkmcnt(0)
	v_mfma_f32_16x16x32_bf16 v[92:95], v[124:127], v[8:11], v[92:95]
	v_mfma_f32_16x16x32_bf16 v[8:11], v[208:211], v[8:11], v[176:179]
	v_mfma_f32_16x16x32_bf16 v[140:143], v[204:207], v[16:19], v[92:95]
	v_mfma_f32_16x16x32_bf16 v[92:95], v[154:157], v[16:19], v[8:11]
	v_mfma_f32_16x16x32_bf16 v[8:11], v[124:127], v[24:27], v[84:87]
	v_mfma_f32_16x16x32_bf16 v[116:119], v[204:207], v[40:43], v[8:11]
	v_mfma_f32_16x16x32_bf16 v[8:11], v[208:211], v[24:27], v[180:183]
	v_mfma_f32_16x16x32_bf16 v[84:87], v[154:157], v[40:43], v[8:11]
	v_mfma_f32_16x16x32_bf16 v[8:11], v[124:127], v[48:51], v[76:79]
	v_mfma_f32_16x16x32_bf16 v[108:111], v[204:207], v[56:59], v[8:11]
	v_mfma_f32_16x16x32_bf16 v[8:11], v[208:211], v[48:51], v[184:187]
	v_mfma_f32_16x16x32_bf16 v[76:79], v[154:157], v[56:59], v[8:11]
	v_mfma_f32_16x16x32_bf16 v[8:11], v[124:127], v[196:199], v[188:191]
	v_mfma_f32_16x16x32_bf16 v[96:99], v[204:207], v[200:203], v[8:11]
	v_mfma_f32_16x16x32_bf16 v[8:11], v[208:211], v[196:199], v[64:67]
	v_mfma_f32_16x16x32_bf16 v[64:67], v[154:157], v[200:203], v[8:11]
	s_barrier
	ds_read_b128 v[176:179], v153 offset:49152
	ds_read_b128 v[180:183], v153 offset:50176
	ds_read_b128 v[184:187], v152 offset:49152
	ds_read_b128 v[188:191], v152 offset:50176
	ds_read_b128 v[196:199], v151 offset:49152
	ds_read_b128 v[200:203], v151 offset:50176
	ds_read_b128 v[212:215], v150 offset:49152
	ds_read_b128 v[150:153], v150 offset:50176
	s_barrier
	s_waitcnt lgkmcnt(0)
	s_waitcnt lgkmcnt(0)
	v_mfma_f32_16x16x32_bf16 v[8:11], v[4:7], v[176:179], v[60:63]
	v_mfma_f32_16x16x32_bf16 v[56:59], v[172:175], v[180:183], v[8:11]
	v_mfma_f32_16x16x32_bf16 v[8:11], v[192:195], v[176:179], v[220:223]
	v_mfma_f32_16x16x32_bf16 v[24:27], v[158:161], v[180:183], v[8:11]
	v_mfma_f32_16x16x32_bf16 v[8:11], v[4:7], v[184:187], v[52:55]
	v_mfma_f32_16x16x32_bf16 v[48:51], v[172:175], v[188:191], v[8:11]
	v_mfma_f32_16x16x32_bf16 v[8:11], v[192:195], v[184:187], v[224:227]
	v_mfma_f32_16x16x32_bf16 v[16:19], v[158:161], v[188:191], v[8:11]
	v_mfma_f32_16x16x32_bf16 v[8:11], v[4:7], v[196:199], v[44:47]
	v_mfma_f32_16x16x32_bf16 v[4:7], v[4:7], v[212:215], v[36:39]
	v_mfma_f32_16x16x32_bf16 v[40:43], v[172:175], v[200:203], v[8:11]
	v_mfma_f32_16x16x32_bf16 v[8:11], v[192:195], v[196:199], v[228:231]
	v_mfma_f32_16x16x32_bf16 v[36:39], v[172:175], v[150:153], v[4:7]
	v_mfma_f32_16x16x32_bf16 v[4:7], v[192:195], v[212:215], v[32:35]
	v_mfma_f32_16x16x32_bf16 v[8:11], v[158:161], v[200:203], v[8:11]
	v_mfma_f32_16x16x32_bf16 v[4:7], v[158:161], v[150:153], v[4:7]
	v_mfma_f32_16x16x32_bf16 v[28:31], v[124:127], v[176:179], v[28:31]
	v_mfma_f32_16x16x32_bf16 v[20:23], v[124:127], v[184:187], v[20:23]
	v_mfma_f32_16x16x32_bf16 v[12:15], v[124:127], v[196:199], v[12:15]
	v_mfma_f32_16x16x32_bf16 v[60:63], v[204:207], v[180:183], v[28:31]
	v_mfma_f32_16x16x32_bf16 v[28:31], v[208:211], v[176:179], v[128:131]
	v_mfma_f32_16x16x32_bf16 v[52:55], v[204:207], v[188:191], v[20:23]
	v_mfma_f32_16x16x32_bf16 v[20:23], v[208:211], v[184:187], v[132:135]
	v_mfma_f32_16x16x32_bf16 v[44:47], v[204:207], v[200:203], v[12:15]
	v_mfma_f32_16x16x32_bf16 v[12:15], v[208:211], v[196:199], v[136:139]
	v_mfma_f32_16x16x32_bf16 v[32:35], v[124:127], v[212:215], v[162:165]
	v_mfma_f32_16x16x32_bf16 v[0:3], v[208:211], v[212:215], v[0:3]
	v_mfma_f32_16x16x32_bf16 v[28:31], v[154:157], v[180:183], v[28:31]
	v_mfma_f32_16x16x32_bf16 v[20:23], v[154:157], v[188:191], v[20:23]
	v_mfma_f32_16x16x32_bf16 v[12:15], v[154:157], v[200:203], v[12:15]
	v_mfma_f32_16x16x32_bf16 v[32:35], v[204:207], v[150:153], v[32:35]
	v_mfma_f32_16x16x32_bf16 v[0:3], v[154:157], v[150:153], v[0:3]
	v_cmp_gt_u32_e64 s[4:5], s84, v145
	s_barrier
	s_and_saveexec_b64 s[8:9], s[4:5]
	s_cbranch_execz .LBB0_1239
	s_barrier

; #define WAIT_V(n) asm volatile("s_waitcnt vmcnt(" #n ")" ::: "memory")
; #define WAIT_L(n) asm volatile("s_waitcnt lgkmcnt(" #n ")" ::: "memory")
; #define BAR __builtin_amdgcn_s_barrier()
; #define SCHED __builtin_amdgcn_sched_barrier(0)
;     ...
;     LDB(B0, 0, 0); SCHED; LDA(At, 0, 0); STAGE(SA(1, 1), A, brow + HALF, t + 1);
;     WAIT_L(8); BAR; WAIT_L(0); MMA(0, 0, At, B0); BAR; SCHED;
;     LDB(B1, 0, 1); STAGE(SB(0, 0), Bt, bcol, t + 2);
;     BAR; WAIT_L(0); MMA(0, 1, At, B1); BAR;
;     LDA(At, 0, 1); STAGE(SA(0, 0), A, brow, t + 2);
;     BAR; WAIT_L(0); MMA(1, 0, At, B0); BAR; SCHED;
;     STAGE(SB(0, 1), Bt, bcol1, t + 2);
;     WAIT_V(6); BAR; MMA(1, 1, At, B1); BAR;
.LBB0_1335:
	ds_read_b128 v[172:175], v169
	ds_read_b128 v[176:179], v169 offset:1024
	ds_read_b128 v[180:183], v169 offset:2048
	ds_read_b128 v[184:187], v169 offset:3072
	v_add_u32_e32 v170, 0xc000, v155
	v_add_u32_e32 v171, 0xe000, v155
	s_add_u32 m0, s23, 0xc000
	ds_read_b128 v[188:191], v151
	ds_read_b128 v[192:195], v151 offset:1024
	ds_read_b128 v[196:199], v150
	ds_read_b128 v[200:203], v150 offset:1024
	ds_read_b128 v[204:207], v145
	ds_read_b128 v[208:211], v145 offset:1024
	ds_read_b128 v[212:215], v144
	ds_read_b128 v[216:219], v144 offset:1024
	global_load_lds_dwordx4 v158, s[64:65]
	s_add_u32 s64, s64, 0x100
	s_addc_u32 s65, s65, 0
	s_add_u32 m0, s23, 0xe000
	s_nop 0
	global_load_lds_dwordx4 v159, s[66:67]
	s_add_u32 s66, s66, 0x100
	s_addc_u32 s67, s67, 0
	s_waitcnt lgkmcnt(8)
	s_barrier
	s_waitcnt lgkmcnt(0)
	v_mfma_f32_16x16x32_bf16 v[124:127], v[172:175], v[188:191], v[124:127]
	v_mfma_f32_16x16x32_bf16 v[120:123], v[180:183], v[188:191], v[120:123]
	v_mfma_f32_16x16x32_bf16 v[116:119], v[172:175], v[196:199], v[116:119]
	v_mfma_f32_16x16x32_bf16 v[112:115], v[180:183], v[196:199], v[112:115]
	v_mfma_f32_16x16x32_bf16 v[108:111], v[172:175], v[204:207], v[108:111]
	v_mfma_f32_16x16x32_bf16 v[104:107], v[180:183], v[204:207], v[104:107]
	v_mfma_f32_16x16x32_bf16 v[100:103], v[172:175], v[212:215], v[100:103]
	v_mfma_f32_16x16x32_bf16 v[96:99], v[180:183], v[212:215], v[96:99]
	v_mfma_f32_16x16x32_bf16 v[124:127], v[176:179], v[192:195], v[124:127]
	v_mfma_f32_16x16x32_bf16 v[120:123], v[184:187], v[192:195], v[120:123]
	v_mfma_f32_16x16x32_bf16 v[116:119], v[176:179], v[200:203], v[116:119]
	v_mfma_f32_16x16x32_bf16 v[112:115], v[184:187], v[200:203], v[112:115]
	v_mfma_f32_16x16x32_bf16 v[108:111], v[176:179], v[208:211], v[108:111]
	v_mfma_f32_16x16x32_bf16 v[104:107], v[184:187], v[208:211], v[104:107]
	v_mfma_f32_16x16x32_bf16 v[100:103], v[176:179], v[216:219], v[100:103]
	v_mfma_f32_16x16x32_bf16 v[96:99], v[184:187], v[216:219], v[96:99]
	s_barrier
	s_add_u32 m0, s23, s33
	ds_read_b128 v[220:223], v168
	ds_read_b128 v[224:227], v168 offset:1024
	ds_read_b128 v[228:231], v168 offset:2048
	ds_read_b128 v[232:235], v168 offset:3072
	global_load_lds_dwordx4 v156, s[68:69]
	s_add_u32 s68, s68, 0x100
	s_addc_u32 s69, s69, 0
	s_add_u32 m0, s23, 0x2000
	s_add_u32 m0, m0, s33
	s_nop 0
	global_load_lds_dwordx4 v157, s[70:71]
	s_add_u32 s70, s70, 0x100
	s_addc_u32 s71, s71, 0
	s_barrier
	s_waitcnt lgkmcnt(0)
	v_mfma_f32_16x16x32_bf16 v[92:95], v[220:223], v[188:191], v[92:95]
	v_mfma_f32_16x16x32_bf16 v[88:91], v[228:231], v[188:191], v[88:91]
	v_mfma_f32_16x16x32_bf16 v[84:87], v[220:223], v[196:199], v[84:87]
	v_mfma_f32_16x16x32_bf16 v[80:83], v[228:231], v[196:199], v[80:83]
	v_mfma_f32_16x16x32_bf16 v[76:79], v[220:223], v[204:207], v[76:79]
	v_mfma_f32_16x16x32_bf16 v[72:75], v[228:231], v[204:207], v[72:75]
	v_mfma_f32_16x16x32_bf16 v[68:71], v[220:223], v[212:215], v[68:71]
	v_mfma_f32_16x16x32_bf16 v[64:67], v[228:231], v[212:215], v[64:67]
	v_mfma_f32_16x16x32_bf16 v[92:95], v[224:227], v[192:195], v[92:95]
	v_mfma_f32_16x16x32_bf16 v[88:91], v[232:235], v[192:195], v[88:91]
	v_mfma_f32_16x16x32_bf16 v[84:87], v[224:227], v[200:203], v[84:87]
	v_mfma_f32_16x16x32_bf16 v[80:83], v[232:235], v[200:203], v[80:83]
	v_mfma_f32_16x16x32_bf16 v[76:79], v[224:227], v[208:211], v[76:79]
	v_mfma_f32_16x16x32_bf16 v[72:75], v[232:235], v[208:211], v[72:75]
	v_mfma_f32_16x16x32_bf16 v[68:71], v[224:227], v[216:219], v[68:71]
	v_mfma_f32_16x16x32_bf16 v[64:67], v[232:235], v[216:219], v[64:67]
	s_mov_b32 m0, s23
	s_barrier
	ds_read_b128 v[188:191], v151 offset:16384
	ds_read_b128 v[192:195], v151 offset:17408
	ds_read_b128 v[196:199], v150 offset:16384
	ds_read_b128 v[200:203], v150 offset:17408
	ds_read_b128 v[204:207], v145 offset:16384
	ds_read_b128 v[208:211], v145 offset:17408
	ds_read_b128 v[212:215], v144 offset:16384
	ds_read_b128 v[216:219], v144 offset:17408
	global_load_lds_dwordx4 v158, s[72:73]
	s_add_u32 s72, s72, 0x100
	s_addc_u32 s73, s73, 0
	s_add_u32 m0, s23, 0x2000
	s_nop 0
	global_load_lds_dwordx4 v159, s[74:75]
	s_add_u32 s74, s74, 0x100
	s_addc_u32 s75, s75, 0
	s_barrier
	s_waitcnt lgkmcnt(0)
	v_mfma_f32_16x16x32_bf16 v[60:63], v[172:175], v[188:191], v[60:63]
	v_mfma_f32_16x16x32_bf16 v[56:59], v[180:183], v[188:191], v[56:59]
	v_mfma_f32_16x16x32_bf16 v[52:55], v[172:175], v[196:199], v[52:55]
	v_mfma_f32_16x16x32_bf16 v[48:51], v[180:183], v[196:199], v[48:51]
	v_mfma_f32_16x16x32_bf16 v[44:47], v[172:175], v[204:207], v[44:47]
	v_mfma_f32_16x16x32_bf16 v[40:43], v[180:183], v[204:207], v[40:43]
	v_mfma_f32_16x16x32_bf16 v[36:39], v[172:175], v[212:215], v[36:39]
	v_mfma_f32_16x16x32_bf16 v[32:35], v[180:183], v[212:215], v[32:35]
	v_mfma_f32_16x16x32_bf16 v[60:63], v[176:179], v[192:195], v[60:63]
	v_mfma_f32_16x16x32_bf16 v[56:59], v[184:187], v[192:195], v[56:59]
	v_mfma_f32_16x16x32_bf16 v[52:55], v[176:179], v[200:203], v[52:55]
	v_mfma_f32_16x16x32_bf16 v[48:51], v[184:187], v[200:203], v[48:51]
	v_mfma_f32_16x16x32_bf16 v[44:47], v[176:179], v[208:211], v[44:47]
	v_mfma_f32_16x16x32_bf16 v[40:43], v[184:187], v[208:211], v[40:43]
	v_mfma_f32_16x16x32_bf16 v[36:39], v[176:179], v[216:219], v[36:39]
	v_mfma_f32_16x16x32_bf16 v[32:35], v[184:187], v[216:219], v[32:35]
	s_barrier
	s_add_u32 m0, s23, s58
	s_nop 0
	global_load_lds_dwordx4 v156, s[76:77]
	s_add_u32 s76, s76, 0x100
	s_addc_u32 s77, s77, 0
	s_add_u32 m0, s23, 0x2000
	s_add_u32 m0, m0, s58
	s_nop 0
	global_load_lds_dwordx4 v157, s[78:79]
	s_add_u32 s78, s78, 0x100
	s_addc_u32 s79, s79, 0
	s_waitcnt vmcnt(6)
	s_barrier
; #define WAIT_V(n) asm volatile("s_waitcnt vmcnt(" #n ")" ::: "memory")
; #define WAIT_L(n) asm volatile("s_waitcnt lgkmcnt(" #n ")" ::: "memory")
; #define BAR __builtin_amdgcn_s_barrier()
; #define SCHED __builtin_amdgcn_sched_barrier(0)
;     ...
;     WAIT_V(6); BAR; MMA(1, 1, At, B1); BAR;
;     LDB(B0, 1, 0); SCHED; LDA(At, 1, 0); STAGE(SA(0, 1), A, brow + HALF, t + 2);
;     WAIT_L(8); BAR; WAIT_L(0); MMA(0, 0, At, B0); BAR; SCHED;
;     LDB(B1, 1, 1); STAGE(SB(1, 0), Bt, bcol, t + 3);
;     BAR; WAIT_L(0); MMA(0, 1, At, B1); BAR;
;     LDA(At, 1, 1); STAGE(SA(1, 0), A, brow, t + 3);
	v_mfma_f32_16x16x32_bf16 v[28:31], v[220:223], v[188:191], v[28:31]
	v_mfma_f32_16x16x32_bf16 v[24:27], v[228:231], v[188:191], v[24:27]
	v_mfma_f32_16x16x32_bf16 v[20:23], v[220:223], v[196:199], v[20:23]
	v_mfma_f32_16x16x32_bf16 v[16:19], v[228:231], v[196:199], v[16:19]
	v_mfma_f32_16x16x32_bf16 v[12:15], v[220:223], v[204:207], v[12:15]
	v_mfma_f32_16x16x32_bf16 v[8:11], v[228:231], v[204:207], v[8:11]
	v_mfma_f32_16x16x32_bf16 v[4:7], v[220:223], v[212:215], v[4:7]
	v_mfma_f32_16x16x32_bf16 v[0:3], v[228:231], v[212:215], v[0:3]
	v_mfma_f32_16x16x32_bf16 v[28:31], v[224:227], v[192:195], v[28:31]
	v_mfma_f32_16x16x32_bf16 v[24:27], v[232:235], v[192:195], v[24:27]
	v_mfma_f32_16x16x32_bf16 v[20:23], v[224:227], v[200:203], v[20:23]
	v_mfma_f32_16x16x32_bf16 v[16:19], v[232:235], v[200:203], v[16:19]
	v_mfma_f32_16x16x32_bf16 v[12:15], v[224:227], v[208:211], v[12:15]
	v_mfma_f32_16x16x32_bf16 v[8:11], v[232:235], v[208:211], v[8:11]
	v_mfma_f32_16x16x32_bf16 v[4:7], v[224:227], v[216:219], v[4:7]
	v_mfma_f32_16x16x32_bf16 v[0:3], v[232:235], v[216:219], v[0:3]
	s_barrier
	ds_read_b128 v[172:175], v160
	ds_read_b128 v[176:179], v160 offset:1024
	ds_read_b128 v[180:183], v160 offset:2048
	ds_read_b128 v[184:187], v160 offset:3072
	s_add_u32 m0, s23, 0x4000
	ds_read_b128 v[188:191], v151 offset:32768
	ds_read_b128 v[192:195], v151 offset:33792
	ds_read_b128 v[196:199], v150 offset:32768
	ds_read_b128 v[200:203], v150 offset:33792
	ds_read_b128 v[204:207], v145 offset:32768
	ds_read_b128 v[208:211], v145 offset:33792
	ds_read_b128 v[212:215], v144 offset:32768
	ds_read_b128 v[216:219], v144 offset:33792
	global_load_lds_dwordx4 v158, s[80:81]
	s_add_u32 s80, s80, 0x100
	s_addc_u32 s81, s81, 0
	s_add_u32 m0, s23, 0x6000
	s_nop 0
	global_load_lds_dwordx4 v159, s[82:83]
	s_add_u32 s82, s82, 0x100
	s_addc_u32 s83, s83, 0
	s_waitcnt lgkmcnt(8)
	s_barrier
	s_waitcnt lgkmcnt(0)
	v_mfma_f32_16x16x32_bf16 v[124:127], v[172:175], v[188:191], v[124:127]
	v_mfma_f32_16x16x32_bf16 v[120:123], v[180:183], v[188:191], v[120:123]
	v_mfma_f32_16x16x32_bf16 v[116:119], v[172:175], v[196:199], v[116:119]
	v_mfma_f32_16x16x32_bf16 v[112:115], v[180:183], v[196:199], v[112:115]
	v_mfma_f32_16x16x32_bf16 v[108:111], v[172:175], v[204:207], v[108:111]
	v_mfma_f32_16x16x32_bf16 v[104:107], v[180:183], v[204:207], v[104:107]
	v_mfma_f32_16x16x32_bf16 v[100:103], v[172:175], v[212:215], v[100:103]
	v_mfma_f32_16x16x32_bf16 v[96:99], v[180:183], v[212:215], v[96:99]
	v_mfma_f32_16x16x32_bf16 v[124:127], v[176:179], v[192:195], v[124:127]
	v_mfma_f32_16x16x32_bf16 v[120:123], v[184:187], v[192:195], v[120:123]
	v_mfma_f32_16x16x32_bf16 v[116:119], v[176:179], v[200:203], v[116:119]
	v_mfma_f32_16x16x32_bf16 v[112:115], v[184:187], v[200:203], v[112:115]
	v_mfma_f32_16x16x32_bf16 v[108:111], v[176:179], v[208:211], v[108:111]
	v_mfma_f32_16x16x32_bf16 v[104:107], v[184:187], v[208:211], v[104:107]
	v_mfma_f32_16x16x32_bf16 v[100:103], v[176:179], v[216:219], v[100:103]
	v_mfma_f32_16x16x32_bf16 v[96:99], v[184:187], v[216:219], v[96:99]
	s_barrier
	s_add_u32 m0, s23, s59
	ds_read_b128 v[220:223], v154
	ds_read_b128 v[224:227], v154 offset:1024
	ds_read_b128 v[228:231], v154 offset:2048
	ds_read_b128 v[232:235], v154 offset:3072
	global_load_lds_dwordx4 v156, s[84:85]
	s_add_u32 s84, s84, 0x100
	s_addc_u32 s85, s85, 0
	s_add_u32 m0, s23, 0x2000
	s_add_u32 m0, m0, s59
	s_nop 0
	global_load_lds_dwordx4 v157, s[86:87]
	s_add_u32 s86, s86, 0x100
	s_addc_u32 s87, s87, 0
	s_barrier
	s_waitcnt lgkmcnt(0)
	v_mfma_f32_16x16x32_bf16 v[92:95], v[220:223], v[188:191], v[92:95]
	v_mfma_f32_16x16x32_bf16 v[88:91], v[228:231], v[188:191], v[88:91]
	v_mfma_f32_16x16x32_bf16 v[84:87], v[220:223], v[196:199], v[84:87]
	v_mfma_f32_16x16x32_bf16 v[80:83], v[228:231], v[196:199], v[80:83]
	v_mfma_f32_16x16x32_bf16 v[76:79], v[220:223], v[204:207], v[76:79]
	v_mfma_f32_16x16x32_bf16 v[72:75], v[228:231], v[204:207], v[72:75]
	v_mfma_f32_16x16x32_bf16 v[68:71], v[220:223], v[212:215], v[68:71]
	v_mfma_f32_16x16x32_bf16 v[64:67], v[228:231], v[212:215], v[64:67]
	v_mfma_f32_16x16x32_bf16 v[92:95], v[224:227], v[192:195], v[92:95]
	v_mfma_f32_16x16x32_bf16 v[88:91], v[232:235], v[192:195], v[88:91]
	v_mfma_f32_16x16x32_bf16 v[84:87], v[224:227], v[200:203], v[84:87]
	v_mfma_f32_16x16x32_bf16 v[80:83], v[232:235], v[200:203], v[80:83]
	v_mfma_f32_16x16x32_bf16 v[76:79], v[224:227], v[208:211], v[76:79]
	v_mfma_f32_16x16x32_bf16 v[72:75], v[232:235], v[208:211], v[72:75]
	v_mfma_f32_16x16x32_bf16 v[68:71], v[224:227], v[216:219], v[68:71]
	v_mfma_f32_16x16x32_bf16 v[64:67], v[232:235], v[216:219], v[64:67]
	s_add_u32 m0, s23, 0x8000
	s_barrier
	ds_read_b128 v[188:191], v151 offset:49152
	ds_read_b128 v[192:195], v151 offset:50176
	ds_read_b128 v[196:199], v150 offset:49152
	ds_read_b128 v[200:203], v150 offset:50176
	ds_read_b128 v[204:207], v145 offset:49152
	ds_read_b128 v[208:211], v145 offset:50176
	ds_read_b128 v[212:215], v144 offset:49152
	ds_read_b128 v[216:219], v144 offset:50176
	global_load_lds_dwordx4 v158, s[88:89]
	s_add_u32 s88, s88, 0x100
	s_addc_u32 s89, s89, 0
	s_add_u32 m0, s23, 0xa000
	s_nop 0
	global_load_lds_dwordx4 v159, s[90:91]
	s_add_u32 s90, s90, 0x100
	s_addc_u32 s91, s91, 0
	s_barrier
; #define WAIT_V(n) asm volatile("s_waitcnt vmcnt(" #n ")" ::: "memory")
; #define WAIT_L(n) asm volatile("s_waitcnt lgkmcnt(" #n ")" ::: "memory")
; #define BAR __builtin_amdgcn_s_barrier()
; #define SCHED __builtin_amdgcn_sched_barrier(0)
;     ...
;     BAR; WAIT_L(0); MMA(0, 1, At, B1); BAR;
;     LDA(At, 1, 1); STAGE(SA(1, 0), A, brow, t + 3);
;     BAR; WAIT_L(0); MMA(1, 0, At, B0); BAR; SCHED;
;     STAGE(SB(1, 1), Bt, bcol1, t + 3);
;     WAIT_V(6); BAR; MMA(1, 1, At, B1); BAR;
;   }
;   { LDB(B0, 0, 0); LDA(At, 0, 0); STAGE(SA(1, 1), A, brow + HALF, nt - 1);
;     BAR; WAIT_L(0); MMA(0, 0, At, B0); BAR;
;     LDB(B1, 0, 1); BAR; WAIT_L(0); MMA(0, 1, At, B1); BAR;
	s_waitcnt lgkmcnt(0)
	v_mfma_f32_16x16x32_bf16 v[60:63], v[172:175], v[188:191], v[60:63]
	v_mfma_f32_16x16x32_bf16 v[56:59], v[180:183], v[188:191], v[56:59]
	v_mfma_f32_16x16x32_bf16 v[52:55], v[172:175], v[196:199], v[52:55]
	v_mfma_f32_16x16x32_bf16 v[48:51], v[180:183], v[196:199], v[48:51]
	v_mfma_f32_16x16x32_bf16 v[44:47], v[172:175], v[204:207], v[44:47]
	v_mfma_f32_16x16x32_bf16 v[40:43], v[180:183], v[204:207], v[40:43]
	v_mfma_f32_16x16x32_bf16 v[36:39], v[172:175], v[212:215], v[36:39]
	v_mfma_f32_16x16x32_bf16 v[32:35], v[180:183], v[212:215], v[32:35]
	v_mfma_f32_16x16x32_bf16 v[60:63], v[176:179], v[192:195], v[60:63]
	v_mfma_f32_16x16x32_bf16 v[56:59], v[184:187], v[192:195], v[56:59]
	v_mfma_f32_16x16x32_bf16 v[52:55], v[176:179], v[200:203], v[52:55]
	v_mfma_f32_16x16x32_bf16 v[48:51], v[184:187], v[200:203], v[48:51]
	v_mfma_f32_16x16x32_bf16 v[44:47], v[176:179], v[208:211], v[44:47]
	v_mfma_f32_16x16x32_bf16 v[40:43], v[184:187], v[208:211], v[40:43]
	v_mfma_f32_16x16x32_bf16 v[36:39], v[176:179], v[216:219], v[36:39]
	v_mfma_f32_16x16x32_bf16 v[32:35], v[184:187], v[216:219], v[32:35]
	s_barrier
	s_add_u32 m0, s23, s60
	s_nop 0
	global_load_lds_dwordx4 v156, s[92:93]
	s_add_u32 s92, s92, 0x100
	s_addc_u32 s93, s93, 0
	s_add_u32 m0, s23, 0x2000
	s_add_u32 m0, m0, s60
	s_nop 0
	global_load_lds_dwordx4 v157, s[94:95]
	s_add_u32 s94, s94, 0x100
	s_addc_u32 s95, s95, 0
	s_waitcnt vmcnt(6)
	s_barrier
	v_mfma_f32_16x16x32_bf16 v[28:31], v[220:223], v[188:191], v[28:31]
	v_mfma_f32_16x16x32_bf16 v[24:27], v[228:231], v[188:191], v[24:27]
	v_mfma_f32_16x16x32_bf16 v[20:23], v[220:223], v[196:199], v[20:23]
	v_mfma_f32_16x16x32_bf16 v[16:19], v[228:231], v[196:199], v[16:19]
	v_mfma_f32_16x16x32_bf16 v[12:15], v[220:223], v[204:207], v[12:15]
	v_mfma_f32_16x16x32_bf16 v[8:11], v[228:231], v[204:207], v[8:11]
	v_mfma_f32_16x16x32_bf16 v[4:7], v[220:223], v[212:215], v[4:7]
	v_mfma_f32_16x16x32_bf16 v[0:3], v[228:231], v[212:215], v[0:3]
	v_mfma_f32_16x16x32_bf16 v[28:31], v[224:227], v[192:195], v[28:31]
	v_mfma_f32_16x16x32_bf16 v[24:27], v[232:235], v[192:195], v[24:27]
	v_mfma_f32_16x16x32_bf16 v[20:23], v[224:227], v[200:203], v[20:23]
	v_mfma_f32_16x16x32_bf16 v[16:19], v[232:235], v[200:203], v[16:19]
	v_mfma_f32_16x16x32_bf16 v[12:15], v[224:227], v[208:211], v[12:15]
	v_mfma_f32_16x16x32_bf16 v[8:11], v[232:235], v[208:211], v[8:11]
	v_mfma_f32_16x16x32_bf16 v[4:7], v[224:227], v[216:219], v[4:7]
	v_mfma_f32_16x16x32_bf16 v[0:3], v[232:235], v[216:219], v[0:3]
	s_add_i32 s22, s22, 2
	s_add_u32 s6, s6, 0x100
	s_addc_u32 s7, s7, 0
	s_cmpk_lt_u32 s22, 0xa8
	s_barrier
	s_cbranch_scc1 .LBB0_1335
	v_readlane_b32 s64, v254, 0
	v_readlane_b32 s65, v254, 1
	v_readlane_b32 s66, v254, 2
	v_readlane_b32 s67, v254, 3
	v_readlane_b32 s68, v254, 4
	v_readlane_b32 s69, v254, 5
	v_readlane_b32 s70, v254, 6
	v_readlane_b32 s71, v254, 7
	v_readlane_b32 s72, v254, 8
	v_readlane_b32 s73, v254, 9
	v_readlane_b32 s74, v254, 10
	v_readlane_b32 s75, v254, 11
	v_readlane_b32 s76, v254, 12
	v_readlane_b32 s77, v254, 13
	v_readlane_b32 s78, v254, 14
	v_readlane_b32 s79, v254, 15
	v_readlane_b32 s80, v254, 16
	v_readlane_b32 s81, v254, 17
	v_readlane_b32 s82, v254, 18
	v_readlane_b32 s83, v254, 19
	v_readlane_b32 s84, v254, 20
	v_readlane_b32 s85, v254, 21
	v_readlane_b32 s86, v254, 22
	v_readlane_b32 s87, v254, 23
	v_readlane_b32 s88, v254, 24
	v_readlane_b32 s89, v254, 25
	v_readlane_b32 s90, v254, 26
	v_readlane_b32 s91, v254, 27
	v_readlane_b32 s92, v254, 28
	v_readlane_b32 s93, v254, 29
	v_readlane_b32 s94, v254, 30
	v_readlane_b32 s95, v254, 31
	s_nop 4
	s_add_u32 s4, s4, 0x5580
	s_addc_u32 s5, s5, 0
	v_readfirstlane_b32 s6, v170
	v_lshl_add_u64 v[152:153], s[4:5], 0, v[128:129]
	s_mov_b32 m0, s6
	v_lshl_add_u64 v[130:131], s[4:5], 0, v[130:131]
	v_readfirstlane_b32 s4, v171
	ds_read_b128 v[132:135], v169
	ds_read_b128 v[136:139], v169 offset:1024
	ds_read_b128 v[156:159], v169 offset:2048
	ds_read_b128 v[162:165], v169 offset:3072
	ds_read_b128 v[172:175], v151
	ds_read_b128 v[176:179], v151 offset:1024
	ds_read_b128 v[180:183], v150
	ds_read_b128 v[184:187], v150 offset:1024
	ds_read_b128 v[188:191], v145
	ds_read_b128 v[192:195], v145 offset:1024
	ds_read_b128 v[196:199], v144
	ds_read_b128 v[200:203], v144 offset:1024
	global_load_lds_dwordx4 v[152:153], off
	s_mov_b32 m0, s4
	s_nop 0
	global_load_lds_dwordx4 v[130:131], off
	s_barrier
	s_waitcnt lgkmcnt(0)
	s_waitcnt lgkmcnt(0)
	v_mfma_f32_16x16x32_bf16 v[124:127], v[132:135], v[172:175], v[124:127]
	v_mfma_f32_16x16x32_bf16 v[120:123], v[156:159], v[172:175], v[120:123]
	v_mfma_f32_16x16x32_bf16 v[108:111], v[132:135], v[188:191], v[108:111]
	v_mfma_f32_16x16x32_bf16 v[104:107], v[156:159], v[188:191], v[104:107]
	v_mfma_f32_16x16x32_bf16 v[124:127], v[136:139], v[176:179], v[124:127]
	v_mfma_f32_16x16x32_bf16 v[120:123], v[162:165], v[176:179], v[120:123]
	v_mfma_f32_16x16x32_bf16 v[116:119], v[132:135], v[180:183], v[116:119]
	v_mfma_f32_16x16x32_bf16 v[112:115], v[156:159], v[180:183], v[112:115]
	v_mfma_f32_16x16x32_bf16 v[108:111], v[136:139], v[192:195], v[108:111]
	v_mfma_f32_16x16x32_bf16 v[104:107], v[162:165], v[192:195], v[104:107]
	v_mfma_f32_16x16x32_bf16 v[100:103], v[132:135], v[196:199], v[100:103]
	v_mfma_f32_16x16x32_bf16 v[96:99], v[156:159], v[196:199], v[96:99]
	v_mfma_f32_16x16x32_bf16 v[204:207], v[136:139], v[184:187], v[116:119]
	v_mfma_f32_16x16x32_bf16 v[208:211], v[162:165], v[184:187], v[112:115]
	v_mfma_f32_16x16x32_bf16 v[212:215], v[136:139], v[200:203], v[100:103]
	v_mfma_f32_16x16x32_bf16 v[216:219], v[162:165], v[200:203], v[96:99]
	s_barrier
; #define WAIT_V(n) asm volatile("s_waitcnt vmcnt(" #n ")" ::: "memory")
; #define WAIT_L(n) asm volatile("s_waitcnt lgkmcnt(" #n ")" ::: "memory")
; #define BAR __builtin_amdgcn_s_barrier()
;     ...
;   { LDB(B0, 0, 0); LDA(At, 0, 0); STAGE(SA(1, 1), A, brow + HALF, nt - 1);
;     BAR; WAIT_L(0); MMA(0, 0, At, B0); BAR;
;     LDB(B1, 0, 1); BAR; WAIT_L(0); MMA(0, 1, At, B1); BAR;
;     LDA(At, 0, 1); WAIT_V(4); BAR; WAIT_L(0); MMA(1, 0, At, B0); MMA(1, 1, At, B1); BAR; }
;   { LDB(B0, 1, 0); LDA(At, 1, 0); WAIT_V(2); BAR; WAIT_L(0); MMA(0, 0, At, B0); BAR;
	s_nop 1
	ds_read_b128 v[96:99], v168
	ds_read_b128 v[100:103], v168 offset:1024
	ds_read_b128 v[112:115], v168 offset:2048
	ds_read_b128 v[116:119], v168 offset:3072
	s_barrier
	s_waitcnt lgkmcnt(0)
	s_waitcnt lgkmcnt(0)
	v_mfma_f32_16x16x32_bf16 v[92:95], v[96:99], v[172:175], v[92:95]
	v_mfma_f32_16x16x32_bf16 v[88:91], v[112:115], v[172:175], v[88:91]
	v_mfma_f32_16x16x32_bf16 v[76:79], v[96:99], v[188:191], v[76:79]
	v_mfma_f32_16x16x32_bf16 v[72:75], v[112:115], v[188:191], v[72:75]
	v_mfma_f32_16x16x32_bf16 v[92:95], v[100:103], v[176:179], v[92:95]
	v_mfma_f32_16x16x32_bf16 v[88:91], v[116:119], v[176:179], v[88:91]
	v_mfma_f32_16x16x32_bf16 v[84:87], v[96:99], v[180:183], v[84:87]
	v_mfma_f32_16x16x32_bf16 v[80:83], v[112:115], v[180:183], v[80:83]
	v_mfma_f32_16x16x32_bf16 v[76:79], v[100:103], v[192:195], v[76:79]
	v_mfma_f32_16x16x32_bf16 v[72:75], v[116:119], v[192:195], v[72:75]
	v_mfma_f32_16x16x32_bf16 v[68:71], v[96:99], v[196:199], v[68:71]
	v_mfma_f32_16x16x32_bf16 v[64:67], v[112:115], v[196:199], v[64:67]
	v_mfma_f32_16x16x32_bf16 v[166:169], v[100:103], v[184:187], v[84:87]
	v_mfma_f32_16x16x32_bf16 v[170:173], v[116:119], v[184:187], v[80:83]
	v_mfma_f32_16x16x32_bf16 v[174:177], v[100:103], v[200:203], v[68:71]
	v_mfma_f32_16x16x32_bf16 v[178:181], v[116:119], v[200:203], v[64:67]
	s_barrier
	s_nop 1
	ds_read_b128 v[64:67], v151 offset:16384
	ds_read_b128 v[68:71], v151 offset:17408
	ds_read_b128 v[80:83], v150 offset:16384
	ds_read_b128 v[84:87], v150 offset:17408
	ds_read_b128 v[182:185], v145 offset:16384
	ds_read_b128 v[186:189], v145 offset:17408
	ds_read_b128 v[190:193], v144 offset:16384
	ds_read_b128 v[194:197], v144 offset:17408
	s_waitcnt vmcnt(4)
	s_barrier
	s_waitcnt lgkmcnt(0)
	s_waitcnt lgkmcnt(0)
	v_mfma_f32_16x16x32_bf16 v[60:63], v[132:135], v[64:67], v[60:63]
	v_mfma_f32_16x16x32_bf16 v[56:59], v[156:159], v[64:67], v[56:59]
	v_mfma_f32_16x16x32_bf16 v[44:47], v[132:135], v[182:185], v[44:47]
	v_mfma_f32_16x16x32_bf16 v[40:43], v[156:159], v[182:185], v[40:43]
	v_mfma_f32_16x16x32_bf16 v[60:63], v[136:139], v[68:71], v[60:63]
	v_mfma_f32_16x16x32_bf16 v[56:59], v[162:165], v[68:71], v[56:59]
	v_mfma_f32_16x16x32_bf16 v[52:55], v[132:135], v[80:83], v[52:55]
	v_mfma_f32_16x16x32_bf16 v[48:51], v[156:159], v[80:83], v[48:51]
	v_mfma_f32_16x16x32_bf16 v[44:47], v[136:139], v[186:189], v[44:47]
	v_mfma_f32_16x16x32_bf16 v[40:43], v[162:165], v[186:189], v[40:43]
	v_mfma_f32_16x16x32_bf16 v[36:39], v[132:135], v[190:193], v[36:39]
	v_mfma_f32_16x16x32_bf16 v[32:35], v[156:159], v[190:193], v[32:35]
	v_mfma_f32_16x16x32_bf16 v[198:201], v[136:139], v[84:87], v[52:55]
	v_mfma_f32_16x16x32_bf16 v[220:223], v[162:165], v[84:87], v[48:51]
	v_mfma_f32_16x16x32_bf16 v[130:133], v[136:139], v[194:197], v[36:39]
	v_mfma_f32_16x16x32_bf16 v[134:137], v[162:165], v[194:197], v[32:35]
	v_mfma_f32_16x16x32_bf16 v[28:31], v[96:99], v[64:67], v[28:31]
	v_mfma_f32_16x16x32_bf16 v[24:27], v[112:115], v[64:67], v[24:27]
	v_mfma_f32_16x16x32_bf16 v[12:15], v[96:99], v[182:185], v[12:15]
	v_mfma_f32_16x16x32_bf16 v[8:11], v[112:115], v[182:185], v[8:11]
	v_mfma_f32_16x16x32_bf16 v[28:31], v[100:103], v[68:71], v[28:31]
	v_mfma_f32_16x16x32_bf16 v[24:27], v[116:119], v[68:71], v[24:27]
	v_mfma_f32_16x16x32_bf16 v[20:23], v[96:99], v[80:83], v[20:23]
	v_mfma_f32_16x16x32_bf16 v[16:19], v[112:115], v[80:83], v[16:19]
	v_mfma_f32_16x16x32_bf16 v[12:15], v[100:103], v[186:189], v[12:15]
	v_mfma_f32_16x16x32_bf16 v[8:11], v[116:119], v[186:189], v[8:11]
	v_mfma_f32_16x16x32_bf16 v[4:7], v[96:99], v[190:193], v[4:7]
	v_mfma_f32_16x16x32_bf16 v[0:3], v[112:115], v[190:193], v[0:3]
	v_mfma_f32_16x16x32_bf16 v[156:159], v[100:103], v[84:87], v[20:23]
	v_mfma_f32_16x16x32_bf16 v[162:165], v[116:119], v[84:87], v[16:19]
	v_mfma_f32_16x16x32_bf16 v[182:185], v[100:103], v[194:197], v[4:7]
	v_mfma_f32_16x16x32_bf16 v[186:189], v[116:119], v[194:197], v[0:3]
	s_barrier
	s_nop 1
	ds_read_b128 v[0:3], v160
	ds_read_b128 v[4:7], v160 offset:1024
	ds_read_b128 v[190:193], v160 offset:2048
	ds_read_b128 v[194:197], v160 offset:3072
	ds_read_b128 v[16:19], v151 offset:32768
	ds_read_b128 v[20:23], v151 offset:33792
	ds_read_b128 v[32:35], v150 offset:32768
	ds_read_b128 v[36:39], v150 offset:33792
	ds_read_b128 v[48:51], v145 offset:32768
	ds_read_b128 v[52:55], v145 offset:33792
	ds_read_b128 v[224:227], v144 offset:32768
	ds_read_b128 v[228:231], v144 offset:33792
	s_waitcnt vmcnt(2)
	s_barrier
; #define WAIT_V(n) asm volatile("s_waitcnt vmcnt(" #n ")" ::: "memory")
; #define WAIT_L(n) asm volatile("s_waitcnt lgkmcnt(" #n ")" ::: "memory")
; #define BAR __builtin_amdgcn_s_barrier()
;     ...
;   { LDB(B0, 1, 0); LDA(At, 1, 0); WAIT_V(2); BAR; WAIT_L(0); MMA(0, 0, At, B0); BAR;
;     LDB(B1, 1, 1); WAIT_V(0); BAR; WAIT_L(0); MMA(0, 1, At, B1); BAR;
;     LDA(At, 1, 1); BAR; WAIT_L(0); MMA(1, 0, At, B0); MMA(1, 1, At, B1); BAR; }
;   if (wr == 0) BAR;
	s_waitcnt lgkmcnt(0)
	s_waitcnt lgkmcnt(0)
	v_mfma_f32_16x16x32_bf16 v[64:67], v[0:3], v[16:19], v[124:127]
	v_mfma_f32_16x16x32_bf16 v[112:115], v[4:7], v[20:23], v[64:67]
	v_mfma_f32_16x16x32_bf16 v[64:67], v[190:193], v[16:19], v[120:123]
	v_mfma_f32_16x16x32_bf16 v[116:119], v[194:197], v[20:23], v[64:67]
	v_mfma_f32_16x16x32_bf16 v[64:67], v[0:3], v[32:35], v[204:207]
	v_mfma_f32_16x16x32_bf16 v[96:99], v[4:7], v[36:39], v[64:67]
	v_mfma_f32_16x16x32_bf16 v[64:67], v[190:193], v[32:35], v[208:211]
	v_mfma_f32_16x16x32_bf16 v[100:103], v[194:197], v[36:39], v[64:67]
	v_mfma_f32_16x16x32_bf16 v[64:67], v[0:3], v[48:51], v[108:111]
	v_mfma_f32_16x16x32_bf16 v[80:83], v[4:7], v[52:55], v[64:67]
	v_mfma_f32_16x16x32_bf16 v[64:67], v[190:193], v[48:51], v[104:107]
	v_mfma_f32_16x16x32_bf16 v[84:87], v[194:197], v[52:55], v[64:67]
	v_mfma_f32_16x16x32_bf16 v[64:67], v[0:3], v[224:227], v[212:215]
	v_mfma_f32_16x16x32_bf16 v[68:71], v[190:193], v[224:227], v[216:219]
	v_mfma_f32_16x16x32_bf16 v[64:67], v[4:7], v[228:231], v[64:67]
	v_mfma_f32_16x16x32_bf16 v[68:71], v[194:197], v[228:231], v[68:71]
	s_barrier
	ds_read_b128 v[202:205], v154
	ds_read_b128 v[206:209], v154 offset:1024
	ds_read_b128 v[210:213], v154 offset:2048
	ds_read_b128 v[152:155], v154 offset:3072
	s_waitcnt vmcnt(0)
	s_barrier
	s_waitcnt lgkmcnt(0)
	s_waitcnt lgkmcnt(0)
	v_mfma_f32_16x16x32_bf16 v[92:95], v[202:205], v[16:19], v[92:95]
	v_mfma_f32_16x16x32_bf16 v[16:19], v[210:213], v[16:19], v[88:91]
	v_mfma_f32_16x16x32_bf16 v[120:123], v[152:155], v[20:23], v[16:19]
	v_mfma_f32_16x16x32_bf16 v[16:19], v[202:205], v[32:35], v[166:169]
	v_mfma_f32_16x16x32_bf16 v[108:111], v[206:209], v[36:39], v[16:19]
	v_mfma_f32_16x16x32_bf16 v[16:19], v[210:213], v[32:35], v[170:173]
	v_mfma_f32_16x16x32_bf16 v[104:107], v[152:155], v[36:39], v[16:19]
	v_mfma_f32_16x16x32_bf16 v[16:19], v[202:205], v[48:51], v[76:79]
	v_mfma_f32_16x16x32_bf16 v[124:127], v[206:209], v[20:23], v[92:95]
	v_mfma_f32_16x16x32_bf16 v[92:95], v[206:209], v[52:55], v[16:19]
	v_mfma_f32_16x16x32_bf16 v[16:19], v[210:213], v[48:51], v[72:75]
	v_mfma_f32_16x16x32_bf16 v[88:91], v[152:155], v[52:55], v[16:19]
	v_mfma_f32_16x16x32_bf16 v[16:19], v[202:205], v[224:227], v[174:177]
	v_mfma_f32_16x16x32_bf16 v[76:79], v[206:209], v[228:231], v[16:19]
	v_mfma_f32_16x16x32_bf16 v[16:19], v[210:213], v[224:227], v[178:181]
	v_mfma_f32_16x16x32_bf16 v[72:75], v[152:155], v[228:231], v[16:19]
	s_barrier
	ds_read_b128 v[166:169], v151 offset:49152
	ds_read_b128 v[170:173], v151 offset:50176
	ds_read_b128 v[174:177], v150 offset:49152
	ds_read_b128 v[178:181], v150 offset:50176
	ds_read_b128 v[214:217], v145 offset:49152
	ds_read_b128 v[224:227], v145 offset:50176
	ds_read_b128 v[228:231], v144 offset:49152
	ds_read_b128 v[232:235], v144 offset:50176
	s_barrier
	s_waitcnt lgkmcnt(0)
	s_waitcnt lgkmcnt(0)
	v_mfma_f32_16x16x32_bf16 v[16:19], v[0:3], v[166:169], v[60:63]
	v_mfma_f32_16x16x32_bf16 v[48:51], v[4:7], v[170:173], v[16:19]
	v_mfma_f32_16x16x32_bf16 v[16:19], v[190:193], v[166:169], v[56:59]
	v_mfma_f32_16x16x32_bf16 v[52:55], v[194:197], v[170:173], v[16:19]
	v_mfma_f32_16x16x32_bf16 v[16:19], v[0:3], v[174:177], v[198:201]
	v_mfma_f32_16x16x32_bf16 v[32:35], v[4:7], v[178:181], v[16:19]
	v_mfma_f32_16x16x32_bf16 v[16:19], v[190:193], v[174:177], v[220:223]
	v_mfma_f32_16x16x32_bf16 v[36:39], v[194:197], v[178:181], v[16:19]
	v_mfma_f32_16x16x32_bf16 v[16:19], v[0:3], v[214:217], v[44:47]
	v_mfma_f32_16x16x32_bf16 v[0:3], v[0:3], v[228:231], v[130:133]
	v_mfma_f32_16x16x32_bf16 v[16:19], v[4:7], v[224:227], v[16:19]
	v_mfma_f32_16x16x32_bf16 v[20:23], v[190:193], v[214:217], v[40:43]
	v_mfma_f32_16x16x32_bf16 v[0:3], v[4:7], v[232:235], v[0:3]
	v_mfma_f32_16x16x32_bf16 v[4:7], v[190:193], v[228:231], v[134:137]
	v_mfma_f32_16x16x32_bf16 v[20:23], v[194:197], v[224:227], v[20:23]
	v_mfma_f32_16x16x32_bf16 v[4:7], v[194:197], v[232:235], v[4:7]
	v_mfma_f32_16x16x32_bf16 v[24:27], v[210:213], v[166:169], v[24:27]
	v_mfma_f32_16x16x32_bf16 v[56:59], v[152:155], v[170:173], v[24:27]
	v_mfma_f32_16x16x32_bf16 v[24:27], v[202:205], v[174:177], v[156:159]
	v_mfma_f32_16x16x32_bf16 v[44:47], v[206:209], v[178:181], v[24:27]
	v_mfma_f32_16x16x32_bf16 v[24:27], v[210:213], v[174:177], v[162:165]
	v_mfma_f32_16x16x32_bf16 v[8:11], v[210:213], v[214:217], v[8:11]
	v_mfma_f32_16x16x32_bf16 v[28:31], v[202:205], v[166:169], v[28:31]
	v_mfma_f32_16x16x32_bf16 v[40:43], v[152:155], v[178:181], v[24:27]
	v_mfma_f32_16x16x32_bf16 v[12:15], v[202:205], v[214:217], v[12:15]
	v_mfma_f32_16x16x32_bf16 v[24:27], v[152:155], v[224:227], v[8:11]
	v_mfma_f32_16x16x32_bf16 v[8:11], v[202:205], v[228:231], v[182:185]
	v_mfma_f32_16x16x32_bf16 v[60:63], v[206:209], v[170:173], v[28:31]
	v_mfma_f32_16x16x32_bf16 v[28:31], v[206:209], v[224:227], v[12:15]
	v_mfma_f32_16x16x32_bf16 v[12:15], v[206:209], v[232:235], v[8:11]
	v_mfma_f32_16x16x32_bf16 v[8:11], v[210:213], v[228:231], v[186:189]
	v_mfma_f32_16x16x32_bf16 v[8:11], v[152:155], v[232:235], v[8:11]
	v_cmp_gt_u32_e32 vcc, s30, v148
	s_barrier
	s_and_saveexec_b64 s[4:5], vcc
	s_cbranch_execz .LBB0_1338
	s_barrier
